# nt hint on the LRU pass-1 per-step (log a, b) table stores (written once, re-read a phase later)
# speedup vs baseline: 1.0032x; 1.0032x over previous
; DI f4 mfma16(h8 a, h8 b, f4 c) { return __builtin_amdgcn_mfma_f32_16x16x32_f16(a, b, c, 0, 0, 0); }
; DI float sigmoidf_(float x) { return 1.f / (1.f + __expf(-x)); }
; DI void lru_tile(const Params& P, int l, int b, int tile, int g, char* smem, bool final, const LruK& K) {
;     ...
;       f4 acc[2][4];
; #pragma unroll
;       for (int gt = 0; gt < 2; gt++)
; #pragma unroll
;         for (int n = 0; n < 4; n++) acc[gt][n] = (f4){0.f, 0.f, 0.f, 0.f};
; #pragma unroll
;       for (int kk = 0; kk < 2; kk++) {
;         int row = wave * 16 + fr;
;         h8 af = *(const h8*)(xr16 + row * 128 + (((kk * 4 + fq) ^ ((row >> 1) & 7)) << 4));
; #pragma unroll
;         for (int gt = 0; gt < 2; gt++)
; #pragma unroll
;           for (int n = 0; n < 4; n++) {
;             int orow = n * 16 + fr;
;             h8 bf = *(const h8*)(Wt + (dir * 2 + gt) * 8192 + orow * 128 + (((kk * 4 + fq) ^ ((orow >> 1) & 7)) << 4));
;             acc[gt][n] = mfma16(af, bf, acc[gt][n]);
;           }
;       }
; #pragma unroll
;       for (int n = 0; n < 4; n++) {
;         const float ba = dir == 0 ? K.ba[0][n] : K.ba[1][n], bx = dir == 0 ? K.bx[0][n] : K.bx[1][n], sp8 = dir == 0 ? K.sp8[0][n] : K.sp8[1][n];
; #pragma unroll
;         for (int j = 0; j < 4; j++) {
;           int tl = wave * 16 + fq * 4 + j, c2 = n * 16 + fr;
;           float xv = (float)*(const half_t*)(xr16 + swz128(tl, c2));
;           float rg = sigmoidf_(acc[0][n][j] + ba), ig = sigmoidf_(acc[1][n][j] + bx);
;           float log_a = rg * sp8;
;           float x2 = 2.f * log_a;
;           float om = -x2 * (1.f + x2 * (0.5f + x2 * (0.16666667f + x2 * (0.041666668f + x2 * (0.008333334f + x2 * 0.0013888889f)))));
;           if (x2 < -0.4f) { float a = __expf(log_a); om = 1.f - a * a; }
;           ab[tl * 64 + c2] = make_float2(log_a, sqrtf(om) * (ig * xv));
.LBB0_401:
	v_add_u32_e32 v6, v55, v57
	ds_read_b128 v[6:9], v6 offset:32768
	v_lshl_or_b32 v14, s20, 14, v54
	v_add_u32_e32 v15, v14, v57
	ds_read_b128 v[10:13], v15
	v_add_u32_e32 v14, v14, v58
	s_waitcnt lgkmcnt(0)
	v_mfma_f32_16x16x32_f16 a[0:3], v[6:9], v[10:13], 0
	ds_read_b128 v[10:13], v15 offset:2048
	s_waitcnt lgkmcnt(0)
	v_mfma_f32_16x16x32_f16 a[4:7], v[6:9], v[10:13], 0
	ds_read_b128 v[10:13], v15 offset:4096
	s_waitcnt lgkmcnt(0)
	v_mfma_f32_16x16x32_f16 a[8:11], v[6:9], v[10:13], 0
	ds_read_b128 v[10:13], v15 offset:6144
	s_waitcnt lgkmcnt(0)
	v_mfma_f32_16x16x32_f16 a[12:15], v[6:9], v[10:13], 0
	ds_read_b128 v[10:13], v15 offset:8192
	s_waitcnt lgkmcnt(0)
	v_mfma_f32_16x16x32_f16 a[20:23], v[6:9], v[10:13], 0
	ds_read_b128 v[10:13], v15 offset:10240
	s_waitcnt lgkmcnt(0)
	v_mfma_f32_16x16x32_f16 a[32:35], v[6:9], v[10:13], 0
	ds_read_b128 v[10:13], v15 offset:12288
	s_waitcnt lgkmcnt(0)
	v_mfma_f32_16x16x32_f16 a[36:39], v[6:9], v[10:13], 0
	ds_read_b128 v[10:13], v15 offset:14336
	s_waitcnt lgkmcnt(0)
	v_mfma_f32_16x16x32_f16 a[40:43], v[6:9], v[10:13], 0
	v_add_u32_e32 v6, v55, v58
	ds_read_b128 v[6:9], v6 offset:32768
	ds_read_b128 v[10:13], v14
	s_waitcnt lgkmcnt(0)
	v_mfma_f32_16x16x32_f16 a[24:27], v[6:9], v[10:13], a[0:3]
	ds_read_b128 v[10:13], v14 offset:2048
	s_waitcnt lgkmcnt(0)
	v_mfma_f32_16x16x32_f16 a[16:19], v[6:9], v[10:13], a[4:7]
	ds_read_b128 v[10:13], v14 offset:4096
	s_waitcnt lgkmcnt(0)
	v_mfma_f32_16x16x32_f16 a[8:11], v[6:9], v[10:13], a[8:11]
	ds_read_b128 v[10:13], v14 offset:6144
	s_waitcnt lgkmcnt(0)
	v_mfma_f32_16x16x32_f16 a[0:3], v[6:9], v[10:13], a[12:15]
	ds_read_b128 v[10:13], v14 offset:8192
	s_waitcnt lgkmcnt(0)
	v_mfma_f32_16x16x32_f16 a[28:31], v[6:9], v[10:13], a[20:23]
	ds_read_b128 v[10:13], v14 offset:10240
	s_waitcnt lgkmcnt(0)
	v_mfma_f32_16x16x32_f16 a[20:23], v[6:9], v[10:13], a[32:35]
	ds_read_b128 v[10:13], v14 offset:12288
	s_waitcnt lgkmcnt(0)
	v_mfma_f32_16x16x32_f16 a[12:15], v[6:9], v[10:13], a[36:39]
	ds_read_b128 v[10:13], v14 offset:14336
	v_cndmask_b32_e64 v14, v37, v25, s[2:3]
	s_waitcnt lgkmcnt(0)
	v_mfma_f32_16x16x32_f16 a[4:7], v[6:9], v[10:13], a[40:43]
	v_accvgpr_read_b32 v10, a28
	v_add_f32_e32 v10, v14, v10
	v_mul_f32_e32 v10, 0xbfb8aa3b, v10
	v_exp_f32_e32 v10, v10
	ds_read_u16 v8, v59 offset:32768
	v_cndmask_b32_e64 v7, v36, v24, s[2:3]
	v_accvgpr_read_b32 v9, a24
	v_add_f32_e32 v10, 1.0, v10
	v_div_scale_f32 v11, s[0:1], v10, v10, 1.0
	v_rcp_f32_e32 v12, v11
	s_waitcnt lgkmcnt(0)
	v_cvt_f32_f16_e32 v8, v8
	v_add_f32_e32 v9, v7, v9
	v_mul_f32_e32 v9, 0xbfb8aa3b, v9
	v_fma_f32 v13, -v11, v12, 1.0
	v_fmac_f32_e32 v12, v13, v12
	v_div_scale_f32 v13, vcc, 1.0, v10, 1.0
	v_mul_f32_e32 v15, v13, v12
	v_fma_f32 v16, -v11, v15, v13
	v_fmac_f32_e32 v15, v16, v12
	v_fma_f32 v11, -v11, v15, v13
	v_div_fmas_f32 v11, v11, v12, v15
	v_div_fixup_f32 v10, v11, v10, 1.0
	v_mul_f32_e32 v12, v10, v8
	v_accvgpr_read_b32 v10, a29
	v_add_f32_e32 v10, v14, v10
	v_mul_f32_e32 v10, 0xbfb8aa3b, v10
	v_exp_f32_e32 v10, v10
	v_accvgpr_read_b32 v8, a25
	v_add_f32_e32 v8, v7, v8
	v_mul_f32_e32 v8, 0xbfb8aa3b, v8
	v_add_f32_e32 v10, 1.0, v10
	v_div_scale_f32 v11, s[0:1], v10, v10, 1.0
	v_rcp_f32_e32 v13, v11
	v_exp_f32_e32 v9, v9
	v_exp_f32_e32 v8, v8
	v_cndmask_b32_e64 v6, v38, v26, s[2:3]
	v_fma_f32 v15, -v11, v13, 1.0
	v_fmac_f32_e32 v13, v15, v13
	v_div_scale_f32 v15, vcc, 1.0, v10, 1.0
	v_mul_f32_e32 v16, v15, v13
	v_fma_f32 v17, -v11, v16, v15
	v_fmac_f32_e32 v16, v17, v13
	v_fma_f32 v11, -v11, v16, v15
	v_div_fmas_f32 v11, v11, v13, v16
	v_pk_add_f32 v[8:9], v[8:9], 1.0 op_sel_hi:[1,0]
	v_div_fixup_f32 v15, v11, v10, 1.0
	v_div_scale_f32 v10, s[0:1], v9, v9, 1.0
	v_rcp_f32_e32 v11, v10
	v_mul_f32_e32 v6, 0xc1000000, v6
	v_fma_f32 v13, -v10, v11, 1.0
	v_fmac_f32_e32 v11, v13, v11
	v_div_scale_f32 v13, vcc, 1.0, v9, 1.0
	v_mul_f32_e32 v16, v13, v11
	v_fma_f32 v17, -v10, v16, v13
	v_fmac_f32_e32 v16, v17, v11
	v_fma_f32 v10, -v10, v16, v13
	v_div_fmas_f32 v10, v10, v11, v16
	v_div_fixup_f32 v9, v10, v9, 1.0
	v_div_scale_f32 v10, s[0:1], v8, v8, 1.0
	v_rcp_f32_e32 v11, v10
	s_nop 0
	v_fma_f32 v13, -v10, v11, 1.0
	v_fmac_f32_e32 v11, v13, v11
	v_div_scale_f32 v13, vcc, 1.0, v8, 1.0
	v_mul_f32_e32 v16, v13, v11
	v_fma_f32 v17, -v10, v16, v13
	v_fmac_f32_e32 v16, v17, v11
	v_fma_f32 v10, -v10, v16, v13
	v_div_fmas_f32 v10, v10, v11, v16
	v_div_fixup_f32 v8, v10, v8, 1.0
	v_pk_mul_f32 v[8:9], v[6:7], v[8:9] op_sel_hi:[0,1]
	v_pk_add_f32 v[10:11], v[8:9], v[8:9]
	v_mul_f32_e32 v16, 0x3fb8aa3b, v9
	v_fmamk_f32 v13, v11, 0x3ab60b61, v177
	v_fmaak_f32 v13, v11, v13, 0x3d2aaaab
	v_exp_f32_e32 v16, v16
	v_fmaak_f32 v13, v11, v13, 0x3e2aaaab
	v_fma_f32 v13, v11, v13, 0.5
	v_fma_f32 v13, v11, v13, 1.0
	v_mul_f32_e64 v13, v13, -v11
	v_fma_f32 v16, -v16, v16, 1.0
	v_cmp_gt_f32_e64 s[0:1], s41, v11
	v_cmp_gt_f32_e32 vcc, s41, v10
	s_nop 0
	v_cndmask_b32_e64 v11, v13, v16, s[0:1]
	v_cmp_gt_f32_e64 s[0:1], s47, v11
	v_mul_f32_e32 v13, 0x4f800000, v11
	s_nop 0
	v_cndmask_b32_e64 v11, v11, v13, s[0:1]
	v_sqrt_f32_e32 v13, v11
	s_nop 0
	v_add_u32_e32 v16, -1, v13
	v_fma_f32 v17, -v16, v13, v11
	v_cmp_ge_f32_e64 s[6:7], 0, v17
	v_add_u32_e32 v17, 1, v13
	s_nop 0
	v_cndmask_b32_e64 v16, v13, v16, s[6:7]
	v_fma_f32 v13, -v17, v13, v11
	v_cmp_lt_f32_e64 s[6:7], 0, v13
	s_nop 1
	v_cndmask_b32_e64 v13, v16, v17, s[6:7]
	v_mul_f32_e32 v16, 0x37800000, v13
	v_cndmask_b32_e64 v13, v13, v16, s[0:1]
	v_cmp_class_f32_e64 s[0:1], v11, v178
	s_nop 1
	v_cndmask_b32_e64 v11, v13, v11, s[0:1]
	v_mul_f32_e32 v13, v12, v11
	v_fmamk_f32 v11, v10, 0x3ab60b61, v177
	v_fmaak_f32 v11, v10, v11, 0x3d2aaaab
	v_fmaak_f32 v11, v10, v11, 0x3e2aaaab
	v_fma_f32 v11, v10, v11, 0.5
	v_fma_f32 v11, v10, v11, 1.0
	v_mul_f32_e64 v10, v11, -v10
	v_mul_f32_e32 v11, 0x3fb8aa3b, v8
	v_exp_f32_e32 v11, v11
	v_mov_b32_e32 v12, v9
	ds_write_b64 v60, v[12:13] offset:40960
	ds_read_u16 v9, v61 offset:32768
	v_fma_f32 v11, -v11, v11, 1.0
	v_cndmask_b32_e32 v10, v10, v11, vcc
	v_cmp_gt_f32_e32 vcc, s47, v10
	v_mul_f32_e32 v11, 0x4f800000, v10
	s_waitcnt lgkmcnt(0)
; DI float sigmoidf_(float x) { return 1.f / (1.f + __expf(-x)); }
; DI void lru_tile(const Params& P, int l, int b, int tile, int g, char* smem, bool final, const LruK& K) {
;     ...
; #pragma unroll
;       for (int n = 0; n < 4; n++) {
;         const float ba = dir == 0 ? K.ba[0][n] : K.ba[1][n], bx = dir == 0 ? K.bx[0][n] : K.bx[1][n], sp8 = dir == 0 ? K.sp8[0][n] : K.sp8[1][n];
; #pragma unroll
;         for (int j = 0; j < 4; j++) {
;           int tl = wave * 16 + fq * 4 + j, c2 = n * 16 + fr;
;           float xv = (float)*(const half_t*)(xr16 + swz128(tl, c2));
;           float rg = sigmoidf_(acc[0][n][j] + ba), ig = sigmoidf_(acc[1][n][j] + bx);
;           float log_a = rg * sp8;
;           float x2 = 2.f * log_a;
;           float om = -x2 * (1.f + x2 * (0.5f + x2 * (0.16666667f + x2 * (0.041666668f + x2 * (0.008333334f + x2 * 0.0013888889f)))));
;           if (x2 < -0.4f) { float a = __expf(log_a); om = 1.f - a * a; }
;           ab[tl * 64 + c2] = make_float2(log_a, sqrtf(om) * (ig * xv));
	v_cvt_f32_f16_e32 v9, v9
	v_cndmask_b32_e32 v10, v10, v11, vcc
	v_sqrt_f32_e32 v11, v10
	v_mul_f32_e32 v9, v15, v9
	v_add_u32_e32 v12, -1, v11
	v_fma_f32 v13, -v12, v11, v10
	v_cmp_ge_f32_e64 s[0:1], 0, v13
	v_add_u32_e32 v13, 1, v11
	s_nop 0
	v_cndmask_b32_e64 v12, v11, v12, s[0:1]
	v_fma_f32 v11, -v13, v11, v10
	v_cmp_lt_f32_e64 s[0:1], 0, v11
	s_nop 1
	v_cndmask_b32_e64 v11, v12, v13, s[0:1]
	v_mul_f32_e32 v12, 0x37800000, v11
	v_cndmask_b32_e32 v11, v11, v12, vcc
	v_cmp_class_f32_e32 vcc, v10, v178
	s_nop 1
	v_cndmask_b32_e32 v10, v11, v10, vcc
	v_mul_f32_e32 v9, v9, v10
	v_accvgpr_read_b32 v10, a30
	v_add_f32_e32 v10, v14, v10
	v_mul_f32_e32 v10, 0xbfb8aa3b, v10
	v_exp_f32_e32 v10, v10
	ds_write_b64 v62, v[8:9] offset:40960
	ds_read_u16 v8, v63 offset:32768
	v_accvgpr_read_b32 v9, a26
	v_add_f32_e32 v10, 1.0, v10
	v_div_scale_f32 v11, s[0:1], v10, v10, 1.0
	v_rcp_f32_e32 v12, v11
	s_waitcnt lgkmcnt(0)
	v_cvt_f32_f16_e32 v8, v8
	v_add_f32_e32 v9, v7, v9
	v_mul_f32_e32 v9, 0xbfb8aa3b, v9
	v_fma_f32 v13, -v11, v12, 1.0
	v_fmac_f32_e32 v12, v13, v12
	v_div_scale_f32 v13, vcc, 1.0, v10, 1.0
	v_mul_f32_e32 v15, v13, v12
	v_fma_f32 v16, -v11, v15, v13
	v_fmac_f32_e32 v15, v16, v12
	v_fma_f32 v11, -v11, v15, v13
	v_div_fmas_f32 v11, v11, v12, v15
	v_div_fixup_f32 v10, v11, v10, 1.0
	v_mul_f32_e32 v10, v10, v8
	v_accvgpr_read_b32 v8, a27
	v_add_f32_e32 v7, v7, v8
	v_mul_f32_e32 v7, 0xbfb8aa3b, v7
	v_exp_f32_e32 v8, v7
	v_accvgpr_read_b32 v7, a31
	v_add_f32_e32 v7, v14, v7
	v_mul_f32_e32 v7, 0xbfb8aa3b, v7
	v_exp_f32_e32 v7, v7
	v_exp_f32_e32 v9, v9
	v_add_f32_e32 v7, 1.0, v7
	v_div_scale_f32 v11, s[0:1], v7, v7, 1.0
	v_rcp_f32_e32 v12, v11
	v_pk_add_f32 v[8:9], v[8:9], 1.0 op_sel_hi:[1,0]
	v_fma_f32 v13, -v11, v12, 1.0
	v_fmac_f32_e32 v12, v13, v12
	v_div_scale_f32 v13, vcc, 1.0, v7, 1.0
	v_mul_f32_e32 v14, v13, v12
	v_fma_f32 v15, -v11, v14, v13
	v_fmac_f32_e32 v14, v15, v12
	v_fma_f32 v11, -v11, v14, v13
	v_div_fmas_f32 v11, v11, v12, v14
	v_div_fixup_f32 v12, v11, v7, 1.0
	v_div_scale_f32 v7, s[0:1], v9, v9, 1.0
	v_rcp_f32_e32 v11, v7
	s_nop 0
	v_fma_f32 v13, -v7, v11, 1.0
	v_fmac_f32_e32 v11, v13, v11
	v_div_scale_f32 v13, vcc, 1.0, v9, 1.0
	v_mul_f32_e32 v14, v13, v11
	v_fma_f32 v15, -v7, v14, v13
	v_fmac_f32_e32 v14, v15, v11
	v_fma_f32 v7, -v7, v14, v13
	v_div_fmas_f32 v7, v7, v11, v14
	v_div_fixup_f32 v9, v7, v9, 1.0
	v_div_scale_f32 v7, s[0:1], v8, v8, 1.0
	v_rcp_f32_e32 v11, v7
	s_nop 0
	v_fma_f32 v13, -v7, v11, 1.0
	v_fmac_f32_e32 v11, v13, v11
	v_div_scale_f32 v13, vcc, 1.0, v8, 1.0
	v_mul_f32_e32 v14, v13, v11
	v_fma_f32 v15, -v7, v14, v13
	v_fmac_f32_e32 v14, v15, v11
	v_fma_f32 v7, -v7, v14, v13
	v_div_fmas_f32 v7, v7, v11, v14
	v_div_fixup_f32 v8, v7, v8, 1.0
	v_pk_mul_f32 v[6:7], v[6:7], v[8:9] op_sel_hi:[0,1]
	v_pk_add_f32 v[8:9], v[6:7], v[6:7]
	v_mul_f32_e32 v13, 0x3fb8aa3b, v7
	v_fmamk_f32 v11, v9, 0x3ab60b61, v177
	v_fmaak_f32 v11, v9, v11, 0x3d2aaaab
	v_exp_f32_e32 v13, v13
	v_fmaak_f32 v11, v9, v11, 0x3e2aaaab
	v_fma_f32 v11, v9, v11, 0.5
	v_fma_f32 v11, v9, v11, 1.0
	v_mul_f32_e64 v11, v11, -v9
	v_fma_f32 v13, -v13, v13, 1.0
	v_cmp_gt_f32_e64 s[0:1], s41, v9
	v_cmp_gt_f32_e32 vcc, s41, v8
	s_nop 0
	v_cndmask_b32_e64 v9, v11, v13, s[0:1]
	v_cmp_gt_f32_e64 s[0:1], s47, v9
	v_mul_f32_e32 v11, 0x4f800000, v9
	s_nop 0
	v_cndmask_b32_e64 v9, v9, v11, s[0:1]
	v_sqrt_f32_e32 v11, v9
	s_nop 0
	v_add_u32_e32 v13, -1, v11
	v_fma_f32 v14, -v13, v11, v9
	v_cmp_ge_f32_e64 s[6:7], 0, v14
	v_add_u32_e32 v14, 1, v11
	s_nop 0
	v_cndmask_b32_e64 v13, v11, v13, s[6:7]
	v_fma_f32 v11, -v14, v11, v9
	v_cmp_lt_f32_e64 s[6:7], 0, v11
	s_nop 1
	v_cndmask_b32_e64 v11, v13, v14, s[6:7]
	v_mul_f32_e32 v13, 0x37800000, v11
	v_cndmask_b32_e64 v11, v11, v13, s[0:1]
	v_cmp_class_f32_e64 s[0:1], v9, v178
	v_cndmask_b32_e64 v14, v40, v28, s[2:3]
	s_nop 0
	v_cndmask_b32_e64 v9, v11, v9, s[0:1]
	v_mul_f32_e32 v11, v9, v10
	v_fmamk_f32 v9, v8, 0x3ab60b61, v177
	v_fmaak_f32 v9, v8, v9, 0x3d2aaaab
	v_fmaak_f32 v9, v8, v9, 0x3e2aaaab
	v_fma_f32 v9, v8, v9, 0.5
	v_fma_f32 v9, v8, v9, 1.0
	v_mul_f32_e64 v8, v9, -v8
	v_mul_f32_e32 v9, 0x3fb8aa3b, v6
	v_exp_f32_e32 v9, v9
	v_mov_b32_e32 v10, v7
	ds_write_b64 v64, v[10:11] offset:40960
	ds_read_u16 v7, v65 offset:32768
	v_fma_f32 v9, -v9, v9, 1.0
	v_cndmask_b32_e32 v8, v8, v9, vcc
	v_cmp_gt_f32_e32 vcc, s47, v8
	v_mul_f32_e32 v9, 0x4f800000, v8
	s_waitcnt lgkmcnt(0)
	v_cvt_f32_f16_e32 v7, v7
	v_cndmask_b32_e32 v8, v8, v9, vcc
	v_sqrt_f32_e32 v9, v8
	v_mul_f32_e32 v7, v12, v7
	v_add_u32_e32 v10, -1, v9
	v_fma_f32 v11, -v10, v9, v8
	v_cmp_ge_f32_e64 s[0:1], 0, v11
	v_add_u32_e32 v11, 1, v9
	s_nop 0
	v_cndmask_b32_e64 v10, v9, v10, s[0:1]
	v_fma_f32 v9, -v11, v9, v8
	v_cmp_lt_f32_e64 s[0:1], 0, v9
	s_nop 1
	v_cndmask_b32_e64 v9, v10, v11, s[0:1]
	v_mul_f32_e32 v10, 0x37800000, v9
	v_cndmask_b32_e32 v9, v9, v10, vcc
	v_accvgpr_read_b32 v10, a20
	v_add_f32_e32 v10, v14, v10
	v_mul_f32_e32 v10, 0xbfb8aa3b, v10
	v_exp_f32_e32 v10, v10
	v_cmp_class_f32_e32 vcc, v8, v178
	v_add_f32_e32 v10, 1.0, v10
	v_div_scale_f32 v11, s[0:1], v10, v10, 1.0
	v_cndmask_b32_e32 v8, v9, v8, vcc
	v_rcp_f32_e32 v12, v11
	v_mul_f32_e32 v7, v8, v7
	ds_write_b64 v66, v[6:7] offset:40960
	ds_read_u16 v8, v67 offset:32768
	v_fma_f32 v13, -v11, v12, 1.0
	v_fmac_f32_e32 v12, v13, v12
	v_div_scale_f32 v13, vcc, 1.0, v10, 1.0
	v_mul_f32_e32 v15, v13, v12
	v_fma_f32 v16, -v11, v15, v13
	s_waitcnt lgkmcnt(0)
; DI float sigmoidf_(float x) { return 1.f / (1.f + __expf(-x)); }
; DI void lru_tile(const Params& P, int l, int b, int tile, int g, char* smem, bool final, const LruK& K) {
;     ...
; #pragma unroll
;       for (int n = 0; n < 4; n++) {
;         const float ba = dir == 0 ? K.ba[0][n] : K.ba[1][n], bx = dir == 0 ? K.bx[0][n] : K.bx[1][n], sp8 = dir == 0 ? K.sp8[0][n] : K.sp8[1][n];
; #pragma unroll
;         for (int j = 0; j < 4; j++) {
;           int tl = wave * 16 + fq * 4 + j, c2 = n * 16 + fr;
;           float xv = (float)*(const half_t*)(xr16 + swz128(tl, c2));
;           float rg = sigmoidf_(acc[0][n][j] + ba), ig = sigmoidf_(acc[1][n][j] + bx);
;           float log_a = rg * sp8;
;           float x2 = 2.f * log_a;
;           float om = -x2 * (1.f + x2 * (0.5f + x2 * (0.16666667f + x2 * (0.041666668f + x2 * (0.008333334f + x2 * 0.0013888889f)))));
;           if (x2 < -0.4f) { float a = __expf(log_a); om = 1.f - a * a; }
;           ab[tl * 64 + c2] = make_float2(log_a, sqrtf(om) * (ig * xv));
	v_cvt_f32_f16_e32 v8, v8
	v_fmac_f32_e32 v15, v16, v12
	v_fma_f32 v11, -v11, v15, v13
	v_div_fmas_f32 v11, v11, v12, v15
	v_div_fixup_f32 v10, v11, v10, 1.0
	v_mul_f32_e32 v12, v10, v8
	v_accvgpr_read_b32 v10, a21
	v_add_f32_e32 v10, v14, v10
	v_mul_f32_e32 v10, 0xbfb8aa3b, v10
	v_exp_f32_e32 v10, v10
	v_cndmask_b32_e64 v7, v39, v27, s[2:3]
	v_accvgpr_read_b32 v9, a16
	v_accvgpr_read_b32 v8, a17
	v_add_f32_e32 v10, 1.0, v10
	v_div_scale_f32 v11, s[0:1], v10, v10, 1.0
	v_rcp_f32_e32 v13, v11
	v_add_f32_e32 v9, v7, v9
	v_add_f32_e32 v8, v7, v8
	v_mul_f32_e32 v9, 0xbfb8aa3b, v9
	v_fma_f32 v15, -v11, v13, 1.0
	v_mul_f32_e32 v8, 0xbfb8aa3b, v8
	v_fmac_f32_e32 v13, v15, v13
	v_div_scale_f32 v15, vcc, 1.0, v10, 1.0
	v_exp_f32_e32 v9, v9
	v_exp_f32_e32 v8, v8
	v_mul_f32_e32 v16, v15, v13
	v_fma_f32 v17, -v11, v16, v15
	v_fmac_f32_e32 v16, v17, v13
	v_fma_f32 v11, -v11, v16, v15
	v_div_fmas_f32 v11, v11, v13, v16
	v_pk_add_f32 v[8:9], v[8:9], 1.0 op_sel_hi:[1,0]
	v_div_fixup_f32 v15, v11, v10, 1.0
	v_div_scale_f32 v10, s[0:1], v9, v9, 1.0
	v_rcp_f32_e32 v11, v10
	v_cndmask_b32_e64 v6, v41, v29, s[2:3]
	v_mul_f32_e32 v6, 0xc1000000, v6
	v_fma_f32 v13, -v10, v11, 1.0
	v_fmac_f32_e32 v11, v13, v11
	v_div_scale_f32 v13, vcc, 1.0, v9, 1.0
	v_mul_f32_e32 v16, v13, v11
	v_fma_f32 v17, -v10, v16, v13
	v_fmac_f32_e32 v16, v17, v11
	v_fma_f32 v10, -v10, v16, v13
	v_div_fmas_f32 v10, v10, v11, v16
	v_div_fixup_f32 v9, v10, v9, 1.0
	v_div_scale_f32 v10, s[0:1], v8, v8, 1.0
	v_rcp_f32_e32 v11, v10
	s_nop 0
	v_fma_f32 v13, -v10, v11, 1.0
	v_fmac_f32_e32 v11, v13, v11
	v_div_scale_f32 v13, vcc, 1.0, v8, 1.0
	v_mul_f32_e32 v16, v13, v11
	v_fma_f32 v17, -v10, v16, v13
	v_fmac_f32_e32 v16, v17, v11
	v_fma_f32 v10, -v10, v16, v13
	v_div_fmas_f32 v10, v10, v11, v16
	v_div_fixup_f32 v8, v10, v8, 1.0
	v_pk_mul_f32 v[8:9], v[6:7], v[8:9] op_sel_hi:[0,1]
	v_pk_add_f32 v[10:11], v[8:9], v[8:9]
	v_mul_f32_e32 v16, 0x3fb8aa3b, v9
	v_fmamk_f32 v13, v11, 0x3ab60b61, v177
	v_fmaak_f32 v13, v11, v13, 0x3d2aaaab
	v_exp_f32_e32 v16, v16
	v_fmaak_f32 v13, v11, v13, 0x3e2aaaab
	v_fma_f32 v13, v11, v13, 0.5
	v_fma_f32 v13, v11, v13, 1.0
	v_mul_f32_e64 v13, v13, -v11
	v_fma_f32 v16, -v16, v16, 1.0
	v_cmp_gt_f32_e64 s[0:1], s41, v11
	v_cmp_gt_f32_e32 vcc, s41, v10
	s_nop 0
	v_cndmask_b32_e64 v11, v13, v16, s[0:1]
	v_cmp_gt_f32_e64 s[0:1], s47, v11
	v_mul_f32_e32 v13, 0x4f800000, v11
	s_nop 0
	v_cndmask_b32_e64 v11, v11, v13, s[0:1]
	v_sqrt_f32_e32 v13, v11
	s_nop 0
	v_add_u32_e32 v16, -1, v13
	v_fma_f32 v17, -v16, v13, v11
	v_cmp_ge_f32_e64 s[6:7], 0, v17
	v_add_u32_e32 v17, 1, v13
	s_nop 0
	v_cndmask_b32_e64 v16, v13, v16, s[6:7]
	v_fma_f32 v13, -v17, v13, v11
	v_cmp_lt_f32_e64 s[6:7], 0, v13
	s_nop 1
	v_cndmask_b32_e64 v13, v16, v17, s[6:7]
	v_mul_f32_e32 v16, 0x37800000, v13
	v_cndmask_b32_e64 v13, v13, v16, s[0:1]
	v_cmp_class_f32_e64 s[0:1], v11, v178
	s_nop 1
	v_cndmask_b32_e64 v11, v13, v11, s[0:1]
	v_mul_f32_e32 v13, v11, v12
	v_fmamk_f32 v11, v10, 0x3ab60b61, v177
	v_fmaak_f32 v11, v10, v11, 0x3d2aaaab
	v_fmaak_f32 v11, v10, v11, 0x3e2aaaab
	v_fma_f32 v11, v10, v11, 0.5
	v_fma_f32 v11, v10, v11, 1.0
	v_mul_f32_e64 v10, v11, -v10
	v_mul_f32_e32 v11, 0x3fb8aa3b, v8
	v_exp_f32_e32 v11, v11
	v_mov_b32_e32 v12, v9
	ds_write_b64 v60, v[12:13] offset:41088
	ds_read_u16 v9, v68 offset:32768
	v_fma_f32 v11, -v11, v11, 1.0
	v_cndmask_b32_e32 v10, v10, v11, vcc
	v_cmp_gt_f32_e32 vcc, s47, v10
	v_mul_f32_e32 v11, 0x4f800000, v10
	s_waitcnt lgkmcnt(0)
	v_cvt_f32_f16_e32 v9, v9
	v_cndmask_b32_e32 v10, v10, v11, vcc
	v_sqrt_f32_e32 v11, v10
	v_mul_f32_e32 v9, v15, v9
	v_add_u32_e32 v12, -1, v11
	v_fma_f32 v13, -v12, v11, v10
	v_cmp_ge_f32_e64 s[0:1], 0, v13
	v_add_u32_e32 v13, 1, v11
	s_nop 0
	v_cndmask_b32_e64 v12, v11, v12, s[0:1]
	v_fma_f32 v11, -v13, v11, v10
	v_cmp_lt_f32_e64 s[0:1], 0, v11
	s_nop 1
	v_cndmask_b32_e64 v11, v12, v13, s[0:1]
	v_mul_f32_e32 v12, 0x37800000, v11
	v_cndmask_b32_e32 v11, v11, v12, vcc
	v_cmp_class_f32_e32 vcc, v10, v178
	s_nop 1
	v_cndmask_b32_e32 v10, v11, v10, vcc
	v_mul_f32_e32 v9, v10, v9
	v_accvgpr_read_b32 v10, a22
	v_add_f32_e32 v10, v14, v10
	v_mul_f32_e32 v10, 0xbfb8aa3b, v10
	v_exp_f32_e32 v10, v10
	ds_write_b64 v62, v[8:9] offset:41088
	ds_read_u16 v8, v69 offset:32768
	v_accvgpr_read_b32 v9, a18
	v_add_f32_e32 v10, 1.0, v10
	v_div_scale_f32 v11, s[0:1], v10, v10, 1.0
	v_rcp_f32_e32 v12, v11
	s_waitcnt lgkmcnt(0)
; DI float sigmoidf_(float x) { return 1.f / (1.f + __expf(-x)); }
; DI void lru_tile(const Params& P, int l, int b, int tile, int g, char* smem, bool final, const LruK& K) {
;     ...
; #pragma unroll
;       for (int n = 0; n < 4; n++) {
;         const float ba = dir == 0 ? K.ba[0][n] : K.ba[1][n], bx = dir == 0 ? K.bx[0][n] : K.bx[1][n], sp8 = dir == 0 ? K.sp8[0][n] : K.sp8[1][n];
; #pragma unroll
;         for (int j = 0; j < 4; j++) {
;           int tl = wave * 16 + fq * 4 + j, c2 = n * 16 + fr;
;           float xv = (float)*(const half_t*)(xr16 + swz128(tl, c2));
;           float rg = sigmoidf_(acc[0][n][j] + ba), ig = sigmoidf_(acc[1][n][j] + bx);
;           float log_a = rg * sp8;
;           float x2 = 2.f * log_a;
;           float om = -x2 * (1.f + x2 * (0.5f + x2 * (0.16666667f + x2 * (0.041666668f + x2 * (0.008333334f + x2 * 0.0013888889f)))));
;           if (x2 < -0.4f) { float a = __expf(log_a); om = 1.f - a * a; }
;           ab[tl * 64 + c2] = make_float2(log_a, sqrtf(om) * (ig * xv));
	v_cvt_f32_f16_e32 v8, v8
	v_add_f32_e32 v9, v7, v9
	v_mul_f32_e32 v9, 0xbfb8aa3b, v9
	v_fma_f32 v13, -v11, v12, 1.0
	v_fmac_f32_e32 v12, v13, v12
	v_div_scale_f32 v13, vcc, 1.0, v10, 1.0
	v_mul_f32_e32 v15, v13, v12
	v_fma_f32 v16, -v11, v15, v13
	v_fmac_f32_e32 v15, v16, v12
	v_fma_f32 v11, -v11, v15, v13
	v_div_fmas_f32 v11, v11, v12, v15
	v_div_fixup_f32 v10, v11, v10, 1.0
	v_mul_f32_e32 v10, v10, v8
	v_accvgpr_read_b32 v8, a19
	v_add_f32_e32 v7, v7, v8
	v_mul_f32_e32 v7, 0xbfb8aa3b, v7
	v_exp_f32_e32 v8, v7
	v_accvgpr_read_b32 v7, a23
	v_add_f32_e32 v7, v14, v7
	v_mul_f32_e32 v7, 0xbfb8aa3b, v7
	v_exp_f32_e32 v7, v7
	v_exp_f32_e32 v9, v9
	v_add_f32_e32 v7, 1.0, v7
	v_div_scale_f32 v11, s[0:1], v7, v7, 1.0
	v_rcp_f32_e32 v12, v11
	v_pk_add_f32 v[8:9], v[8:9], 1.0 op_sel_hi:[1,0]
	v_fma_f32 v13, -v11, v12, 1.0
	v_fmac_f32_e32 v12, v13, v12
	v_div_scale_f32 v13, vcc, 1.0, v7, 1.0
	v_mul_f32_e32 v14, v13, v12
	v_fma_f32 v15, -v11, v14, v13
	v_fmac_f32_e32 v14, v15, v12
	v_fma_f32 v11, -v11, v14, v13
	v_div_fmas_f32 v11, v11, v12, v14
	v_div_fixup_f32 v12, v11, v7, 1.0
	v_div_scale_f32 v7, s[0:1], v9, v9, 1.0
	v_rcp_f32_e32 v11, v7
	s_nop 0
	v_fma_f32 v13, -v7, v11, 1.0
	v_fmac_f32_e32 v11, v13, v11
	v_div_scale_f32 v13, vcc, 1.0, v9, 1.0
	v_mul_f32_e32 v14, v13, v11
	v_fma_f32 v15, -v7, v14, v13
	v_fmac_f32_e32 v14, v15, v11
	v_fma_f32 v7, -v7, v14, v13
	v_div_fmas_f32 v7, v7, v11, v14
	v_div_fixup_f32 v9, v7, v9, 1.0
	v_div_scale_f32 v7, s[0:1], v8, v8, 1.0
	v_rcp_f32_e32 v11, v7
	s_nop 0
	v_fma_f32 v13, -v7, v11, 1.0
	v_fmac_f32_e32 v11, v13, v11
	v_div_scale_f32 v13, vcc, 1.0, v8, 1.0
	v_mul_f32_e32 v14, v13, v11
	v_fma_f32 v15, -v7, v14, v13
	v_fmac_f32_e32 v14, v15, v11
	v_fma_f32 v7, -v7, v14, v13
	v_div_fmas_f32 v7, v7, v11, v14
	v_div_fixup_f32 v8, v7, v8, 1.0
	v_pk_mul_f32 v[6:7], v[6:7], v[8:9] op_sel_hi:[0,1]
	v_pk_add_f32 v[8:9], v[6:7], v[6:7]
	v_mul_f32_e32 v13, 0x3fb8aa3b, v7
	v_fmamk_f32 v11, v9, 0x3ab60b61, v177
	v_fmaak_f32 v11, v9, v11, 0x3d2aaaab
	v_exp_f32_e32 v13, v13
	v_fmaak_f32 v11, v9, v11, 0x3e2aaaab
	v_fma_f32 v11, v9, v11, 0.5
	v_fma_f32 v11, v9, v11, 1.0
	v_mul_f32_e64 v11, v11, -v9
	v_fma_f32 v13, -v13, v13, 1.0
	v_cmp_gt_f32_e64 s[0:1], s41, v9
	v_cmp_gt_f32_e32 vcc, s41, v8
	s_nop 0
	v_cndmask_b32_e64 v9, v11, v13, s[0:1]
	v_cmp_gt_f32_e64 s[0:1], s47, v9
	v_mul_f32_e32 v11, 0x4f800000, v9
	s_nop 0
	v_cndmask_b32_e64 v9, v9, v11, s[0:1]
	v_sqrt_f32_e32 v11, v9
	s_nop 0
	v_add_u32_e32 v13, -1, v11
	v_fma_f32 v14, -v13, v11, v9
	v_cmp_ge_f32_e64 s[6:7], 0, v14
	v_add_u32_e32 v14, 1, v11
	s_nop 0
	v_cndmask_b32_e64 v13, v11, v13, s[6:7]
	v_fma_f32 v11, -v14, v11, v9
	v_cmp_lt_f32_e64 s[6:7], 0, v11
	s_nop 1
	v_cndmask_b32_e64 v11, v13, v14, s[6:7]
	v_mul_f32_e32 v13, 0x37800000, v11
	v_cndmask_b32_e64 v11, v11, v13, s[0:1]
	v_cmp_class_f32_e64 s[0:1], v9, v178
	v_cndmask_b32_e64 v14, v43, v31, s[2:3]
	s_nop 0
	v_cndmask_b32_e64 v9, v11, v9, s[0:1]
	v_mul_f32_e32 v11, v9, v10
	v_fmamk_f32 v9, v8, 0x3ab60b61, v177
	v_fmaak_f32 v9, v8, v9, 0x3d2aaaab
	v_fmaak_f32 v9, v8, v9, 0x3e2aaaab
	v_fma_f32 v9, v8, v9, 0.5
	v_fma_f32 v9, v8, v9, 1.0
	v_mul_f32_e64 v8, v9, -v8
	v_mul_f32_e32 v9, 0x3fb8aa3b, v6
	v_exp_f32_e32 v9, v9
	v_mov_b32_e32 v10, v7
	ds_write_b64 v64, v[10:11] offset:41088
	ds_read_u16 v7, v70 offset:32768
	v_fma_f32 v9, -v9, v9, 1.0
	v_cndmask_b32_e32 v8, v8, v9, vcc
	v_cmp_gt_f32_e32 vcc, s47, v8
	v_mul_f32_e32 v9, 0x4f800000, v8
	s_waitcnt lgkmcnt(0)
	v_cvt_f32_f16_e32 v7, v7
	v_cndmask_b32_e32 v8, v8, v9, vcc
	v_sqrt_f32_e32 v9, v8
	v_mul_f32_e32 v7, v12, v7
	v_add_u32_e32 v10, -1, v9
	v_fma_f32 v11, -v10, v9, v8
	v_cmp_ge_f32_e64 s[0:1], 0, v11
	v_add_u32_e32 v11, 1, v9
	s_nop 0
	v_cndmask_b32_e64 v10, v9, v10, s[0:1]
	v_fma_f32 v9, -v11, v9, v8
	v_cmp_lt_f32_e64 s[0:1], 0, v9
	s_nop 1
	v_cndmask_b32_e64 v9, v10, v11, s[0:1]
	v_mul_f32_e32 v10, 0x37800000, v9
	v_cndmask_b32_e32 v9, v9, v10, vcc
	v_accvgpr_read_b32 v10, a12
	v_add_f32_e32 v10, v14, v10
	v_mul_f32_e32 v10, 0xbfb8aa3b, v10
	v_exp_f32_e32 v10, v10
	v_cmp_class_f32_e32 vcc, v8, v178
	v_add_f32_e32 v10, 1.0, v10
	v_div_scale_f32 v11, s[0:1], v10, v10, 1.0
	v_cndmask_b32_e32 v8, v9, v8, vcc
	v_rcp_f32_e32 v12, v11
	v_mul_f32_e32 v7, v8, v7
	ds_write_b64 v66, v[6:7] offset:41088
	ds_read_u16 v8, v71 offset:32768
	v_fma_f32 v13, -v11, v12, 1.0
	v_fmac_f32_e32 v12, v13, v12
	v_div_scale_f32 v13, vcc, 1.0, v10, 1.0
	v_mul_f32_e32 v15, v13, v12
	v_fma_f32 v16, -v11, v15, v13
	s_waitcnt lgkmcnt(0)
; DI float sigmoidf_(float x) { return 1.f / (1.f + __expf(-x)); }
; DI void lru_tile(const Params& P, int l, int b, int tile, int g, char* smem, bool final, const LruK& K) {
;     ...
; #pragma unroll
;       for (int n = 0; n < 4; n++) {
;         const float ba = dir == 0 ? K.ba[0][n] : K.ba[1][n], bx = dir == 0 ? K.bx[0][n] : K.bx[1][n], sp8 = dir == 0 ? K.sp8[0][n] : K.sp8[1][n];
; #pragma unroll
;         for (int j = 0; j < 4; j++) {
;           int tl = wave * 16 + fq * 4 + j, c2 = n * 16 + fr;
;           float xv = (float)*(const half_t*)(xr16 + swz128(tl, c2));
;           float rg = sigmoidf_(acc[0][n][j] + ba), ig = sigmoidf_(acc[1][n][j] + bx);
;           float log_a = rg * sp8;
;           float x2 = 2.f * log_a;
;           float om = -x2 * (1.f + x2 * (0.5f + x2 * (0.16666667f + x2 * (0.041666668f + x2 * (0.008333334f + x2 * 0.0013888889f)))));
;           if (x2 < -0.4f) { float a = __expf(log_a); om = 1.f - a * a; }
;           ab[tl * 64 + c2] = make_float2(log_a, sqrtf(om) * (ig * xv));
	v_cvt_f32_f16_e32 v8, v8
	v_fmac_f32_e32 v15, v16, v12
	v_fma_f32 v11, -v11, v15, v13
	v_div_fmas_f32 v11, v11, v12, v15
	v_div_fixup_f32 v10, v11, v10, 1.0
	v_mul_f32_e32 v12, v10, v8
	v_accvgpr_read_b32 v10, a13
	v_add_f32_e32 v10, v14, v10
	v_mul_f32_e32 v10, 0xbfb8aa3b, v10
	v_exp_f32_e32 v10, v10
	v_cndmask_b32_e64 v7, v42, v30, s[2:3]
	v_accvgpr_read_b32 v9, a8
	v_accvgpr_read_b32 v8, a9
	v_add_f32_e32 v10, 1.0, v10
	v_div_scale_f32 v11, s[0:1], v10, v10, 1.0
	v_rcp_f32_e32 v13, v11
	v_add_f32_e32 v9, v7, v9
	v_add_f32_e32 v8, v7, v8
	v_mul_f32_e32 v9, 0xbfb8aa3b, v9
	v_fma_f32 v15, -v11, v13, 1.0
	v_mul_f32_e32 v8, 0xbfb8aa3b, v8
	v_fmac_f32_e32 v13, v15, v13
	v_div_scale_f32 v15, vcc, 1.0, v10, 1.0
	v_exp_f32_e32 v9, v9
	v_exp_f32_e32 v8, v8
	v_mul_f32_e32 v16, v15, v13
	v_fma_f32 v17, -v11, v16, v15
	v_fmac_f32_e32 v16, v17, v13
	v_fma_f32 v11, -v11, v16, v15
	v_div_fmas_f32 v11, v11, v13, v16
	v_pk_add_f32 v[8:9], v[8:9], 1.0 op_sel_hi:[1,0]
	v_div_fixup_f32 v15, v11, v10, 1.0
	v_div_scale_f32 v10, s[0:1], v9, v9, 1.0
	v_rcp_f32_e32 v11, v10
	v_cndmask_b32_e64 v6, v44, v32, s[2:3]
	v_mul_f32_e32 v6, 0xc1000000, v6
	v_fma_f32 v13, -v10, v11, 1.0
	v_fmac_f32_e32 v11, v13, v11
	v_div_scale_f32 v13, vcc, 1.0, v9, 1.0
	v_mul_f32_e32 v16, v13, v11
	v_fma_f32 v17, -v10, v16, v13
	v_fmac_f32_e32 v16, v17, v11
	v_fma_f32 v10, -v10, v16, v13
	v_div_fmas_f32 v10, v10, v11, v16
	v_div_fixup_f32 v9, v10, v9, 1.0
	v_div_scale_f32 v10, s[0:1], v8, v8, 1.0
	v_rcp_f32_e32 v11, v10
	s_nop 0
	v_fma_f32 v13, -v10, v11, 1.0
	v_fmac_f32_e32 v11, v13, v11
	v_div_scale_f32 v13, vcc, 1.0, v8, 1.0
	v_mul_f32_e32 v16, v13, v11
	v_fma_f32 v17, -v10, v16, v13
	v_fmac_f32_e32 v16, v17, v11
	v_fma_f32 v10, -v10, v16, v13
	v_div_fmas_f32 v10, v10, v11, v16
	v_div_fixup_f32 v8, v10, v8, 1.0
	v_pk_mul_f32 v[8:9], v[6:7], v[8:9] op_sel_hi:[0,1]
	v_pk_add_f32 v[10:11], v[8:9], v[8:9]
	v_mul_f32_e32 v16, 0x3fb8aa3b, v9
	v_fmamk_f32 v13, v11, 0x3ab60b61, v177
	v_fmaak_f32 v13, v11, v13, 0x3d2aaaab
	v_exp_f32_e32 v16, v16
	v_fmaak_f32 v13, v11, v13, 0x3e2aaaab
	v_fma_f32 v13, v11, v13, 0.5
	v_fma_f32 v13, v11, v13, 1.0
	v_mul_f32_e64 v13, v13, -v11
	v_fma_f32 v16, -v16, v16, 1.0
	v_cmp_gt_f32_e64 s[0:1], s41, v11
	v_cmp_gt_f32_e32 vcc, s41, v10
	s_nop 0
	v_cndmask_b32_e64 v11, v13, v16, s[0:1]
	v_cmp_gt_f32_e64 s[0:1], s47, v11
	v_mul_f32_e32 v13, 0x4f800000, v11
	s_nop 0
	v_cndmask_b32_e64 v11, v11, v13, s[0:1]
	v_sqrt_f32_e32 v13, v11
	s_nop 0
	v_add_u32_e32 v16, -1, v13
	v_fma_f32 v17, -v16, v13, v11
	v_cmp_ge_f32_e64 s[6:7], 0, v17
	v_add_u32_e32 v17, 1, v13
	s_nop 0
	v_cndmask_b32_e64 v16, v13, v16, s[6:7]
	v_fma_f32 v13, -v17, v13, v11
	v_cmp_lt_f32_e64 s[6:7], 0, v13
	s_nop 1
	v_cndmask_b32_e64 v13, v16, v17, s[6:7]
	v_mul_f32_e32 v16, 0x37800000, v13
	v_cndmask_b32_e64 v13, v13, v16, s[0:1]
	v_cmp_class_f32_e64 s[0:1], v11, v178
	s_nop 1
	v_cndmask_b32_e64 v11, v13, v11, s[0:1]
	v_mul_f32_e32 v13, v11, v12
	v_fmamk_f32 v11, v10, 0x3ab60b61, v177
	v_fmaak_f32 v11, v10, v11, 0x3d2aaaab
	v_fmaak_f32 v11, v10, v11, 0x3e2aaaab
	v_fma_f32 v11, v10, v11, 0.5
	v_fma_f32 v11, v10, v11, 1.0
	v_mul_f32_e64 v10, v11, -v10
	v_mul_f32_e32 v11, 0x3fb8aa3b, v8
	v_exp_f32_e32 v11, v11
	v_mov_b32_e32 v12, v9
	ds_write_b64 v60, v[12:13] offset:41216
	ds_read_u16 v9, v72 offset:32768
	v_fma_f32 v11, -v11, v11, 1.0
	v_cndmask_b32_e32 v10, v10, v11, vcc
	v_cmp_gt_f32_e32 vcc, s47, v10
	v_mul_f32_e32 v11, 0x4f800000, v10
	s_waitcnt lgkmcnt(0)
	v_cvt_f32_f16_e32 v9, v9
	v_cndmask_b32_e32 v10, v10, v11, vcc
	v_sqrt_f32_e32 v11, v10
	v_mul_f32_e32 v9, v15, v9
	v_add_u32_e32 v12, -1, v11
	v_fma_f32 v13, -v12, v11, v10
	v_cmp_ge_f32_e64 s[0:1], 0, v13
	v_add_u32_e32 v13, 1, v11
	s_nop 0
	v_cndmask_b32_e64 v12, v11, v12, s[0:1]
	v_fma_f32 v11, -v13, v11, v10
	v_cmp_lt_f32_e64 s[0:1], 0, v11
	s_nop 1
	v_cndmask_b32_e64 v11, v12, v13, s[0:1]
	v_mul_f32_e32 v12, 0x37800000, v11
	v_cndmask_b32_e32 v11, v11, v12, vcc
	v_cmp_class_f32_e32 vcc, v10, v178
	s_nop 1
	v_cndmask_b32_e32 v10, v11, v10, vcc
	v_mul_f32_e32 v9, v10, v9
	v_accvgpr_read_b32 v10, a14
	v_add_f32_e32 v10, v14, v10
	v_mul_f32_e32 v10, 0xbfb8aa3b, v10
	v_exp_f32_e32 v10, v10
	ds_write_b64 v62, v[8:9] offset:41216
	ds_read_u16 v8, v73 offset:32768
	v_accvgpr_read_b32 v9, a10
	v_add_f32_e32 v10, 1.0, v10
	v_div_scale_f32 v11, s[0:1], v10, v10, 1.0
	v_rcp_f32_e32 v12, v11
	s_waitcnt lgkmcnt(0)
; DI float sigmoidf_(float x) { return 1.f / (1.f + __expf(-x)); }
; DI void lru_tile(const Params& P, int l, int b, int tile, int g, char* smem, bool final, const LruK& K) {
;     ...
; #pragma unroll
;       for (int n = 0; n < 4; n++) {
;         const float ba = dir == 0 ? K.ba[0][n] : K.ba[1][n], bx = dir == 0 ? K.bx[0][n] : K.bx[1][n], sp8 = dir == 0 ? K.sp8[0][n] : K.sp8[1][n];
; #pragma unroll
;         for (int j = 0; j < 4; j++) {
;           int tl = wave * 16 + fq * 4 + j, c2 = n * 16 + fr;
;           float xv = (float)*(const half_t*)(xr16 + swz128(tl, c2));
;           float rg = sigmoidf_(acc[0][n][j] + ba), ig = sigmoidf_(acc[1][n][j] + bx);
;           float log_a = rg * sp8;
;           float x2 = 2.f * log_a;
;           float om = -x2 * (1.f + x2 * (0.5f + x2 * (0.16666667f + x2 * (0.041666668f + x2 * (0.008333334f + x2 * 0.0013888889f)))));
;           if (x2 < -0.4f) { float a = __expf(log_a); om = 1.f - a * a; }
;           ab[tl * 64 + c2] = make_float2(log_a, sqrtf(om) * (ig * xv));
	v_cvt_f32_f16_e32 v8, v8
	v_add_f32_e32 v9, v7, v9
	v_mul_f32_e32 v9, 0xbfb8aa3b, v9
	v_fma_f32 v13, -v11, v12, 1.0
	v_fmac_f32_e32 v12, v13, v12
	v_div_scale_f32 v13, vcc, 1.0, v10, 1.0
	v_mul_f32_e32 v15, v13, v12
	v_fma_f32 v16, -v11, v15, v13
	v_fmac_f32_e32 v15, v16, v12
	v_fma_f32 v11, -v11, v15, v13
	v_div_fmas_f32 v11, v11, v12, v15
	v_div_fixup_f32 v10, v11, v10, 1.0
	v_mul_f32_e32 v10, v10, v8
	v_accvgpr_read_b32 v8, a11
	v_add_f32_e32 v7, v7, v8
	v_mul_f32_e32 v7, 0xbfb8aa3b, v7
	v_exp_f32_e32 v8, v7
	v_accvgpr_read_b32 v7, a15
	v_add_f32_e32 v7, v14, v7
	v_mul_f32_e32 v7, 0xbfb8aa3b, v7
	v_exp_f32_e32 v7, v7
	v_exp_f32_e32 v9, v9
	v_add_f32_e32 v7, 1.0, v7
	v_div_scale_f32 v11, s[0:1], v7, v7, 1.0
	v_rcp_f32_e32 v12, v11
	v_pk_add_f32 v[8:9], v[8:9], 1.0 op_sel_hi:[1,0]
	v_fma_f32 v13, -v11, v12, 1.0
	v_fmac_f32_e32 v12, v13, v12
	v_div_scale_f32 v13, vcc, 1.0, v7, 1.0
	v_mul_f32_e32 v14, v13, v12
	v_fma_f32 v15, -v11, v14, v13
	v_fmac_f32_e32 v14, v15, v12
	v_fma_f32 v11, -v11, v14, v13
	v_div_fmas_f32 v11, v11, v12, v14
	v_div_fixup_f32 v12, v11, v7, 1.0
	v_div_scale_f32 v7, s[0:1], v9, v9, 1.0
	v_rcp_f32_e32 v11, v7
	s_nop 0
	v_fma_f32 v13, -v7, v11, 1.0
	v_fmac_f32_e32 v11, v13, v11
	v_div_scale_f32 v13, vcc, 1.0, v9, 1.0
	v_mul_f32_e32 v14, v13, v11
	v_fma_f32 v15, -v7, v14, v13
	v_fmac_f32_e32 v14, v15, v11
	v_fma_f32 v7, -v7, v14, v13
	v_div_fmas_f32 v7, v7, v11, v14
	v_div_fixup_f32 v9, v7, v9, 1.0
	v_div_scale_f32 v7, s[0:1], v8, v8, 1.0
	v_rcp_f32_e32 v11, v7
	s_nop 0
	v_fma_f32 v13, -v7, v11, 1.0
	v_fmac_f32_e32 v11, v13, v11
	v_div_scale_f32 v13, vcc, 1.0, v8, 1.0
	v_mul_f32_e32 v14, v13, v11
	v_fma_f32 v15, -v7, v14, v13
	v_fmac_f32_e32 v14, v15, v11
	v_fma_f32 v7, -v7, v14, v13
	v_div_fmas_f32 v7, v7, v11, v14
	v_div_fixup_f32 v8, v7, v8, 1.0
	v_pk_mul_f32 v[6:7], v[6:7], v[8:9] op_sel_hi:[0,1]
	v_pk_add_f32 v[8:9], v[6:7], v[6:7]
	v_mul_f32_e32 v13, 0x3fb8aa3b, v7
	v_fmamk_f32 v11, v9, 0x3ab60b61, v177
	v_fmaak_f32 v11, v9, v11, 0x3d2aaaab
	v_exp_f32_e32 v13, v13
	v_fmaak_f32 v11, v9, v11, 0x3e2aaaab
	v_fma_f32 v11, v9, v11, 0.5
	v_fma_f32 v11, v9, v11, 1.0
	v_mul_f32_e64 v11, v11, -v9
	v_fma_f32 v13, -v13, v13, 1.0
	v_cmp_gt_f32_e64 s[0:1], s41, v9
	v_cmp_gt_f32_e32 vcc, s41, v8
	s_nop 0
	v_cndmask_b32_e64 v9, v11, v13, s[0:1]
	v_cmp_gt_f32_e64 s[0:1], s47, v9
	v_mul_f32_e32 v11, 0x4f800000, v9
	s_nop 0
	v_cndmask_b32_e64 v9, v9, v11, s[0:1]
	v_sqrt_f32_e32 v11, v9
	s_nop 0
	v_add_u32_e32 v13, -1, v11
	v_fma_f32 v14, -v13, v11, v9
	v_cmp_ge_f32_e64 s[6:7], 0, v14
	v_add_u32_e32 v14, 1, v11
	s_nop 0
	v_cndmask_b32_e64 v13, v11, v13, s[6:7]
	v_fma_f32 v11, -v14, v11, v9
	v_cmp_lt_f32_e64 s[6:7], 0, v11
	s_nop 1
	v_cndmask_b32_e64 v11, v13, v14, s[6:7]
	v_mul_f32_e32 v13, 0x37800000, v11
	v_cndmask_b32_e64 v11, v11, v13, s[0:1]
	v_cmp_class_f32_e64 s[0:1], v9, v178
	v_cndmask_b32_e64 v14, v46, v34, s[2:3]
	s_nop 0
	v_cndmask_b32_e64 v9, v11, v9, s[0:1]
	v_mul_f32_e32 v11, v9, v10
	v_fmamk_f32 v9, v8, 0x3ab60b61, v177
	v_fmaak_f32 v9, v8, v9, 0x3d2aaaab
	v_fmaak_f32 v9, v8, v9, 0x3e2aaaab
	v_fma_f32 v9, v8, v9, 0.5
	v_fma_f32 v9, v8, v9, 1.0
	v_mul_f32_e64 v8, v9, -v8
	v_mul_f32_e32 v9, 0x3fb8aa3b, v6
	v_exp_f32_e32 v9, v9
	v_mov_b32_e32 v10, v7
	ds_write_b64 v64, v[10:11] offset:41216
	ds_read_u16 v7, v74 offset:32768
	v_fma_f32 v9, -v9, v9, 1.0
	v_cndmask_b32_e32 v8, v8, v9, vcc
	v_cmp_gt_f32_e32 vcc, s47, v8
	v_mul_f32_e32 v9, 0x4f800000, v8
	s_waitcnt lgkmcnt(0)
	v_cvt_f32_f16_e32 v7, v7
	v_cndmask_b32_e32 v8, v8, v9, vcc
	v_sqrt_f32_e32 v9, v8
	v_mul_f32_e32 v7, v12, v7
	v_add_u32_e32 v10, -1, v9
	v_fma_f32 v11, -v10, v9, v8
	v_cmp_ge_f32_e64 s[0:1], 0, v11
	v_add_u32_e32 v11, 1, v9
	s_nop 0
	v_cndmask_b32_e64 v10, v9, v10, s[0:1]
	v_fma_f32 v9, -v11, v9, v8
	v_cmp_lt_f32_e64 s[0:1], 0, v9
	s_nop 1
	v_cndmask_b32_e64 v9, v10, v11, s[0:1]
	v_mul_f32_e32 v10, 0x37800000, v9
	v_cndmask_b32_e32 v9, v9, v10, vcc
	v_accvgpr_read_b32 v10, a4
	v_add_f32_e32 v10, v14, v10
	v_mul_f32_e32 v10, 0xbfb8aa3b, v10
	v_exp_f32_e32 v10, v10
	v_cmp_class_f32_e32 vcc, v8, v178
	v_add_f32_e32 v10, 1.0, v10
	v_div_scale_f32 v11, s[0:1], v10, v10, 1.0
	v_cndmask_b32_e32 v8, v9, v8, vcc
	v_rcp_f32_e32 v12, v11
	v_mul_f32_e32 v7, v8, v7
	ds_write_b64 v66, v[6:7] offset:41216
	ds_read_u16 v8, v75 offset:32768
	v_fma_f32 v13, -v11, v12, 1.0
	v_fmac_f32_e32 v12, v13, v12
	v_div_scale_f32 v13, vcc, 1.0, v10, 1.0
	v_mul_f32_e32 v15, v13, v12
	v_fma_f32 v16, -v11, v15, v13
	s_waitcnt lgkmcnt(0)
; DI float sigmoidf_(float x) { return 1.f / (1.f + __expf(-x)); }
; DI void lru_tile(const Params& P, int l, int b, int tile, int g, char* smem, bool final, const LruK& K) {
;     ...
; #pragma unroll
;       for (int n = 0; n < 4; n++) {
;         const float ba = dir == 0 ? K.ba[0][n] : K.ba[1][n], bx = dir == 0 ? K.bx[0][n] : K.bx[1][n], sp8 = dir == 0 ? K.sp8[0][n] : K.sp8[1][n];
; #pragma unroll
;         for (int j = 0; j < 4; j++) {
;           int tl = wave * 16 + fq * 4 + j, c2 = n * 16 + fr;
;           float xv = (float)*(const half_t*)(xr16 + swz128(tl, c2));
;           float rg = sigmoidf_(acc[0][n][j] + ba), ig = sigmoidf_(acc[1][n][j] + bx);
;           float log_a = rg * sp8;
;           float x2 = 2.f * log_a;
;           float om = -x2 * (1.f + x2 * (0.5f + x2 * (0.16666667f + x2 * (0.041666668f + x2 * (0.008333334f + x2 * 0.0013888889f)))));
;           if (x2 < -0.4f) { float a = __expf(log_a); om = 1.f - a * a; }
;           ab[tl * 64 + c2] = make_float2(log_a, sqrtf(om) * (ig * xv));
;         }
;       }
	v_cvt_f32_f16_e32 v8, v8
	v_fmac_f32_e32 v15, v16, v12
	v_fma_f32 v11, -v11, v15, v13
	v_div_fmas_f32 v11, v11, v12, v15
	v_div_fixup_f32 v10, v11, v10, 1.0
	v_mul_f32_e32 v12, v10, v8
	v_accvgpr_read_b32 v10, a5
	v_add_f32_e32 v10, v14, v10
	v_mul_f32_e32 v10, 0xbfb8aa3b, v10
	v_exp_f32_e32 v10, v10
	v_cndmask_b32_e64 v7, v45, v33, s[2:3]
	v_accvgpr_read_b32 v9, a0
	v_accvgpr_read_b32 v8, a1
	v_add_f32_e32 v10, 1.0, v10
	v_div_scale_f32 v11, s[0:1], v10, v10, 1.0
	v_rcp_f32_e32 v13, v11
	v_add_f32_e32 v9, v7, v9
	v_add_f32_e32 v8, v7, v8
	v_mul_f32_e32 v9, 0xbfb8aa3b, v9
	v_fma_f32 v15, -v11, v13, 1.0
	v_mul_f32_e32 v8, 0xbfb8aa3b, v8
	v_fmac_f32_e32 v13, v15, v13
	v_div_scale_f32 v15, vcc, 1.0, v10, 1.0
	v_exp_f32_e32 v9, v9
	v_exp_f32_e32 v8, v8
	v_mul_f32_e32 v16, v15, v13
	v_fma_f32 v17, -v11, v16, v15
	v_fmac_f32_e32 v16, v17, v13
	v_fma_f32 v11, -v11, v16, v15
	v_div_fmas_f32 v11, v11, v13, v16
	v_pk_add_f32 v[8:9], v[8:9], 1.0 op_sel_hi:[1,0]
	v_div_fixup_f32 v15, v11, v10, 1.0
	v_div_scale_f32 v10, s[0:1], v9, v9, 1.0
	v_rcp_f32_e32 v11, v10
	v_cndmask_b32_e64 v6, v47, v35, s[2:3]
	v_mul_f32_e32 v6, 0xc1000000, v6
	v_fma_f32 v13, -v10, v11, 1.0
	v_fmac_f32_e32 v11, v13, v11
	v_div_scale_f32 v13, vcc, 1.0, v9, 1.0
	v_mul_f32_e32 v16, v13, v11
	v_fma_f32 v17, -v10, v16, v13
	v_fmac_f32_e32 v16, v17, v11
	v_fma_f32 v10, -v10, v16, v13
	v_div_fmas_f32 v10, v10, v11, v16
	v_div_fixup_f32 v9, v10, v9, 1.0
	v_div_scale_f32 v10, s[0:1], v8, v8, 1.0
	v_rcp_f32_e32 v11, v10
	s_nop 0
	v_fma_f32 v13, -v10, v11, 1.0
	v_fmac_f32_e32 v11, v13, v11
	v_div_scale_f32 v13, vcc, 1.0, v8, 1.0
	v_mul_f32_e32 v16, v13, v11
	v_fma_f32 v17, -v10, v16, v13
	v_fmac_f32_e32 v16, v17, v11
	v_fma_f32 v10, -v10, v16, v13
	v_div_fmas_f32 v10, v10, v11, v16
	v_div_fixup_f32 v8, v10, v8, 1.0
	v_pk_mul_f32 v[8:9], v[6:7], v[8:9] op_sel_hi:[0,1]
	v_pk_add_f32 v[10:11], v[8:9], v[8:9]
	v_mul_f32_e32 v16, 0x3fb8aa3b, v9
	v_fmamk_f32 v13, v11, 0x3ab60b61, v177
	v_fmaak_f32 v13, v11, v13, 0x3d2aaaab
	v_exp_f32_e32 v16, v16
	v_fmaak_f32 v13, v11, v13, 0x3e2aaaab
	v_fma_f32 v13, v11, v13, 0.5
	v_fma_f32 v13, v11, v13, 1.0
	v_mul_f32_e64 v13, v13, -v11
	v_fma_f32 v16, -v16, v16, 1.0
	v_cmp_gt_f32_e64 s[0:1], s41, v11
	v_cmp_gt_f32_e32 vcc, s41, v10
	s_nop 0
	v_cndmask_b32_e64 v11, v13, v16, s[0:1]
	v_cmp_gt_f32_e64 s[0:1], s47, v11
	v_mul_f32_e32 v13, 0x4f800000, v11
	s_nop 0
	v_cndmask_b32_e64 v11, v11, v13, s[0:1]
	v_sqrt_f32_e32 v13, v11
	s_nop 0
	v_add_u32_e32 v16, -1, v13
	v_fma_f32 v17, -v16, v13, v11
	v_cmp_ge_f32_e64 s[6:7], 0, v17
	v_add_u32_e32 v17, 1, v13
	s_nop 0
	v_cndmask_b32_e64 v16, v13, v16, s[6:7]
	v_fma_f32 v13, -v17, v13, v11
	v_cmp_lt_f32_e64 s[6:7], 0, v13
	s_nop 1
	v_cndmask_b32_e64 v13, v16, v17, s[6:7]
	v_mul_f32_e32 v16, 0x37800000, v13
	v_cndmask_b32_e64 v13, v13, v16, s[0:1]
	v_cmp_class_f32_e64 s[0:1], v11, v178
	s_nop 1
	v_cndmask_b32_e64 v11, v13, v11, s[0:1]
	v_mul_f32_e32 v13, v11, v12
	v_fmamk_f32 v11, v10, 0x3ab60b61, v177
	v_fmaak_f32 v11, v10, v11, 0x3d2aaaab
	v_fmaak_f32 v11, v10, v11, 0x3e2aaaab
	v_fma_f32 v11, v10, v11, 0.5
	v_fma_f32 v11, v10, v11, 1.0
	v_mul_f32_e64 v10, v11, -v10
	v_mul_f32_e32 v11, 0x3fb8aa3b, v8
	v_exp_f32_e32 v11, v11
	v_mov_b32_e32 v12, v9
	ds_write_b64 v60, v[12:13] offset:41344
	ds_read_u16 v9, v76 offset:32768
	v_fma_f32 v11, -v11, v11, 1.0
	v_cndmask_b32_e32 v10, v10, v11, vcc
	v_cmp_gt_f32_e32 vcc, s47, v10
	v_mul_f32_e32 v11, 0x4f800000, v10
	s_waitcnt lgkmcnt(0)
	v_cvt_f32_f16_e32 v9, v9
	v_cndmask_b32_e32 v10, v10, v11, vcc
	v_sqrt_f32_e32 v11, v10
	v_mul_f32_e32 v9, v15, v9
	v_add_u32_e32 v12, -1, v11
	v_fma_f32 v13, -v12, v11, v10
	v_cmp_ge_f32_e64 s[0:1], 0, v13
	v_add_u32_e32 v13, 1, v11
	s_nop 0
	v_cndmask_b32_e64 v12, v11, v12, s[0:1]
	v_fma_f32 v11, -v13, v11, v10
	v_cmp_lt_f32_e64 s[0:1], 0, v11
	s_nop 1
	v_cndmask_b32_e64 v11, v12, v13, s[0:1]
	v_mul_f32_e32 v12, 0x37800000, v11
	v_cndmask_b32_e32 v11, v11, v12, vcc
	v_cmp_class_f32_e32 vcc, v10, v178
	s_nop 1
	v_cndmask_b32_e32 v10, v11, v10, vcc
	v_mul_f32_e32 v9, v10, v9
	v_accvgpr_read_b32 v10, a6
	v_add_f32_e32 v10, v14, v10
	v_mul_f32_e32 v10, 0xbfb8aa3b, v10
	v_exp_f32_e32 v10, v10
	ds_write_b64 v62, v[8:9] offset:41344
	ds_read_u16 v8, v77 offset:32768
	v_accvgpr_read_b32 v9, a2
	v_add_f32_e32 v10, 1.0, v10
	v_div_scale_f32 v11, s[0:1], v10, v10, 1.0
	v_rcp_f32_e32 v12, v11
	s_waitcnt lgkmcnt(0)
; DI float sigmoidf_(float x) { return 1.f / (1.f + __expf(-x)); }
; DI void lru_tile(const Params& P, int l, int b, int tile, int g, char* smem, bool final, const LruK& K) {
;     ...
; #pragma unroll
;       for (int n = 0; n < 4; n++) {
;         const float ba = dir == 0 ? K.ba[0][n] : K.ba[1][n], bx = dir == 0 ? K.bx[0][n] : K.bx[1][n], sp8 = dir == 0 ? K.sp8[0][n] : K.sp8[1][n];
; #pragma unroll
;         for (int j = 0; j < 4; j++) {
;           int tl = wave * 16 + fq * 4 + j, c2 = n * 16 + fr;
;           float xv = (float)*(const half_t*)(xr16 + swz128(tl, c2));
;           float rg = sigmoidf_(acc[0][n][j] + ba), ig = sigmoidf_(acc[1][n][j] + bx);
;           float log_a = rg * sp8;
;           float x2 = 2.f * log_a;
;           float om = -x2 * (1.f + x2 * (0.5f + x2 * (0.16666667f + x2 * (0.041666668f + x2 * (0.008333334f + x2 * 0.0013888889f)))));
;           if (x2 < -0.4f) { float a = __expf(log_a); om = 1.f - a * a; }
;           ab[tl * 64 + c2] = make_float2(log_a, sqrtf(om) * (ig * xv));
;         }
;       }
;     }
;     __syncthreads();
;     {
;       float A = 1.f, h = 0.f;
; #pragma unroll
;       for (int e = 0; e < 16; e++) {
;         const int ee = dir == 0 ? e : 15 - e;
;         const float2 lb = ab[(tq * 16 + ee) * 64 + ch];
;         fp16x2 hv; hv[0] = (__fp16)lb.x; hv[1] = (__fp16)lb.y;
;         lab[((size_t)dir * TA + rowbase + t0 + tq * 16 + ee) * 256 + gc] = __builtin_bit_cast(unsigned, hv);
;         const float a = __expf((float)hv[0]), bt = (float)hv[1];
;         h = a * h + bt; A *= a;
	v_cvt_f32_f16_e32 v8, v8
	v_add_f32_e32 v9, v7, v9
	v_mul_f32_e32 v9, 0xbfb8aa3b, v9
	v_fma_f32 v13, -v11, v12, 1.0
	v_fmac_f32_e32 v12, v13, v12
	v_div_scale_f32 v13, vcc, 1.0, v10, 1.0
	v_mul_f32_e32 v15, v13, v12
	v_fma_f32 v16, -v11, v15, v13
	v_fmac_f32_e32 v15, v16, v12
	v_fma_f32 v11, -v11, v15, v13
	v_div_fmas_f32 v11, v11, v12, v15
	v_div_fixup_f32 v10, v11, v10, 1.0
	v_mul_f32_e32 v10, v10, v8
	v_accvgpr_read_b32 v8, a3
	v_add_f32_e32 v7, v7, v8
	v_mul_f32_e32 v7, 0xbfb8aa3b, v7
	v_exp_f32_e32 v8, v7
	v_accvgpr_read_b32 v7, a7
	v_add_f32_e32 v7, v14, v7
	v_mul_f32_e32 v7, 0xbfb8aa3b, v7
	v_exp_f32_e32 v7, v7
	v_exp_f32_e32 v9, v9
	v_add_f32_e32 v7, 1.0, v7
	v_div_scale_f32 v11, s[0:1], v7, v7, 1.0
	v_rcp_f32_e32 v12, v11
	v_pk_add_f32 v[8:9], v[8:9], 1.0 op_sel_hi:[1,0]
	v_fma_f32 v13, -v11, v12, 1.0
	v_fmac_f32_e32 v12, v13, v12
	v_div_scale_f32 v13, vcc, 1.0, v7, 1.0
	v_mul_f32_e32 v14, v13, v12
	v_fma_f32 v15, -v11, v14, v13
	v_fmac_f32_e32 v14, v15, v12
	v_fma_f32 v11, -v11, v14, v13
	v_div_fmas_f32 v11, v11, v12, v14
	v_div_fixup_f32 v12, v11, v7, 1.0
	v_div_scale_f32 v7, s[0:1], v9, v9, 1.0
	v_rcp_f32_e32 v11, v7
	s_nop 0
	v_fma_f32 v13, -v7, v11, 1.0
	v_fmac_f32_e32 v11, v13, v11
	v_div_scale_f32 v13, vcc, 1.0, v9, 1.0
	v_mul_f32_e32 v14, v13, v11
	v_fma_f32 v15, -v7, v14, v13
	v_fmac_f32_e32 v14, v15, v11
	v_fma_f32 v7, -v7, v14, v13
	v_div_fmas_f32 v7, v7, v11, v14
	v_div_fixup_f32 v9, v7, v9, 1.0
	v_div_scale_f32 v7, s[0:1], v8, v8, 1.0
	v_rcp_f32_e32 v11, v7
	s_nop 0
	v_fma_f32 v13, -v7, v11, 1.0
	v_fmac_f32_e32 v11, v13, v11
	v_div_scale_f32 v13, vcc, 1.0, v8, 1.0
	v_mul_f32_e32 v14, v13, v11
	v_fma_f32 v15, -v7, v14, v13
	v_fmac_f32_e32 v14, v15, v11
	v_fma_f32 v7, -v7, v14, v13
	v_div_fmas_f32 v7, v7, v11, v14
	v_div_fixup_f32 v8, v7, v8, 1.0
	v_pk_mul_f32 v[6:7], v[6:7], v[8:9] op_sel_hi:[0,1]
	v_pk_add_f32 v[8:9], v[6:7], v[6:7]
	v_mul_f32_e32 v13, 0x3fb8aa3b, v7
	v_fmamk_f32 v11, v9, 0x3ab60b61, v177
	v_fmaak_f32 v11, v9, v11, 0x3d2aaaab
	v_exp_f32_e32 v13, v13
	v_fmaak_f32 v11, v9, v11, 0x3e2aaaab
	v_fma_f32 v11, v9, v11, 0.5
	v_fma_f32 v11, v9, v11, 1.0
	v_mul_f32_e64 v11, v11, -v9
	v_fma_f32 v13, -v13, v13, 1.0
	v_cmp_gt_f32_e64 s[0:1], s41, v9
	v_cmp_gt_f32_e32 vcc, s41, v8
	s_nop 0
	v_cndmask_b32_e64 v9, v11, v13, s[0:1]
	v_cmp_gt_f32_e64 s[0:1], s47, v9
	v_mul_f32_e32 v11, 0x4f800000, v9
	s_nop 0
	v_cndmask_b32_e64 v9, v9, v11, s[0:1]
	v_sqrt_f32_e32 v11, v9
	s_nop 0
	v_add_u32_e32 v13, -1, v11
	v_fma_f32 v14, -v13, v11, v9
	v_cmp_ge_f32_e64 s[6:7], 0, v14
	v_add_u32_e32 v14, 1, v11
	s_nop 0
	v_cndmask_b32_e64 v13, v11, v13, s[6:7]
	v_fma_f32 v11, -v14, v11, v9
	v_cmp_lt_f32_e64 s[6:7], 0, v11
	s_nop 1
	v_cndmask_b32_e64 v11, v13, v14, s[6:7]
	v_mul_f32_e32 v13, 0x37800000, v11
	v_cndmask_b32_e64 v11, v11, v13, s[0:1]
	v_cmp_class_f32_e64 s[0:1], v9, v178
	s_nop 1
	v_cndmask_b32_e64 v9, v11, v9, s[0:1]
	v_mul_f32_e32 v11, v9, v10
	v_fmamk_f32 v9, v8, 0x3ab60b61, v177
	v_fmaak_f32 v9, v8, v9, 0x3d2aaaab
	v_fmaak_f32 v9, v8, v9, 0x3e2aaaab
	v_fma_f32 v9, v8, v9, 0.5
	v_fma_f32 v9, v8, v9, 1.0
	v_mul_f32_e64 v8, v9, -v8
	v_mul_f32_e32 v9, 0x3fb8aa3b, v6
	v_exp_f32_e32 v9, v9
	v_mov_b32_e32 v10, v7
	ds_write_b64 v64, v[10:11] offset:41344
	ds_read_u16 v7, v78 offset:32768
	v_fma_f32 v9, -v9, v9, 1.0
	v_cndmask_b32_e32 v8, v8, v9, vcc
	v_cmp_gt_f32_e32 vcc, s47, v8
	v_mul_f32_e32 v9, 0x4f800000, v8
	s_waitcnt lgkmcnt(0)
	v_cvt_f32_f16_e32 v7, v7
	v_cndmask_b32_e32 v8, v8, v9, vcc
	v_sqrt_f32_e32 v9, v8
	v_mul_f32_e32 v7, v12, v7
	v_add_u32_e32 v10, -1, v9
	v_fma_f32 v11, -v10, v9, v8
	v_cmp_ge_f32_e64 s[0:1], 0, v11
	v_add_u32_e32 v11, 1, v9
	s_nop 0
	v_cndmask_b32_e64 v10, v9, v10, s[0:1]
	v_fma_f32 v9, -v11, v9, v8
	v_cmp_lt_f32_e64 s[0:1], 0, v9
	s_nop 1
	v_cndmask_b32_e64 v9, v10, v11, s[0:1]
	s_mul_i32 s0, s20, 0x10800
	v_mul_f32_e32 v10, 0x37800000, v9
	s_add_i32 s84, s0, s10
	v_cndmask_b32_e32 v9, v9, v10, vcc
	v_cmp_class_f32_e32 vcc, v8, v178
	s_and_b64 s[0:1], s[2:3], exec
	s_cselect_b32 s0, 0, 15
	v_cndmask_b32_e32 v8, v9, v8, vcc
	v_mul_f32_e32 v7, v8, v7
	v_or_b32_e32 v8, s0, v0
	v_lshl_or_b32 v8, v8, 9, v56
	ds_write_b64 v66, v[6:7] offset:41344
	s_waitcnt lgkmcnt(0)
	s_barrier
	ds_read_b64 v[8:9], v8 offset:40960
	v_lshl_add_u64 v[6:7], v[2:3], 0, s[84:85]
	s_waitcnt lgkmcnt(0)
	v_cvt_f16_f32_e32 v10, v8
	v_cvt_f16_f32_e32 v11, v9
	v_cvt_pk_f16_f32 v12, v8, v9
	v_or_b32_e32 v8, s0, v6
	v_mov_b32_e32 v9, v7
	v_lshlrev_b64 v[8:9], 10, v[8:9]
	v_lshl_add_u64 v[8:9], v[4:5], 0, v[8:9]
	global_store_dword v[8:9], v12, off nt
	v_cvt_f32_f16_e32 v8, v10
	s_cselect_b32 s0, 1, 14
	v_mul_f32_e32 v8, 0x3fb8aa3b, v8
	v_exp_f32_e32 v10, v8
	v_or_b32_e32 v8, s0, v0
	v_lshl_or_b32 v8, v8, 9, v56
	ds_read_b64 v[8:9], v8 offset:40960
	v_fma_mix_f32 v11, v10, 0, v11 op_sel_hi:[0,0,1]
	s_waitcnt lgkmcnt(0)
	v_cvt_f16_f32_e32 v12, v8
	v_cvt_f16_f32_e32 v13, v9
	v_cvt_pk_f16_f32 v14, v8, v9
	v_or_b32_e32 v8, s0, v6
	v_mov_b32_e32 v9, v7
	v_lshlrev_b64 v[8:9], 10, v[8:9]
	v_lshl_add_u64 v[8:9], v[4:5], 0, v[8:9]
	global_store_dword v[8:9], v14, off nt
	v_cvt_f32_f16_e32 v8, v12
	s_cselect_b32 s0, 2, 13
	v_mul_f32_e32 v8, 0x3fb8aa3b, v8
	v_exp_f32_e32 v8, v8
	s_nop 0
	v_fma_mix_f32 v11, v11, v8, v13 op_sel_hi:[0,0,1]
	v_mul_f32_e32 v14, v10, v8
	v_or_b32_e32 v8, s0, v0
	v_lshl_or_b32 v8, v8, 9, v56
	ds_read_b64 v[8:9], v8 offset:40960
	s_waitcnt lgkmcnt(0)
; DI void lru_tile(const Params& P, int l, int b, int tile, int g, char* smem, bool final, const LruK& K) {
;     ...
; #pragma unroll
;       for (int e = 0; e < 16; e++) {
;         const int ee = dir == 0 ? e : 15 - e;
;         const float2 lb = ab[(tq * 16 + ee) * 64 + ch];
;         fp16x2 hv; hv[0] = (__fp16)lb.x; hv[1] = (__fp16)lb.y;
;         lab[((size_t)dir * TA + rowbase + t0 + tq * 16 + ee) * 256 + gc] = __builtin_bit_cast(unsigned, hv);
;         const float a = __expf((float)hv[0]), bt = (float)hv[1];
;         h = a * h + bt; A *= a;
;       }
	v_cvt_f16_f32_e32 v10, v8
	v_cvt_f16_f32_e32 v12, v9
	v_cvt_pk_f16_f32 v13, v8, v9
	v_or_b32_e32 v8, s0, v6
	v_mov_b32_e32 v9, v7
	v_lshlrev_b64 v[8:9], 10, v[8:9]
	v_lshl_add_u64 v[8:9], v[4:5], 0, v[8:9]
	global_store_dword v[8:9], v13, off nt
	v_cvt_f32_f16_e32 v8, v10
	s_cselect_b32 s0, 3, 12
	v_or_b32_e32 v10, s0, v0
	v_lshl_or_b32 v10, v10, 9, v56
	v_mul_f32_e32 v8, 0x3fb8aa3b, v8
	v_exp_f32_e32 v8, v8
	s_nop 0
	v_fma_mix_f32 v9, v11, v8, v12 op_sel_hi:[0,0,1]
	ds_read_b64 v[10:11], v10 offset:40960
	s_waitcnt lgkmcnt(0)
	v_cvt_f16_f32_e32 v12, v10
	v_cvt_f16_f32_e32 v13, v11
	v_cvt_pk_f16_f32 v15, v10, v11
	v_or_b32_e32 v10, s0, v6
	v_mov_b32_e32 v11, v7
	v_lshlrev_b64 v[10:11], 10, v[10:11]
	v_lshl_add_u64 v[10:11], v[4:5], 0, v[10:11]
	global_store_dword v[10:11], v15, off nt
	v_cvt_f32_f16_e32 v10, v12
	s_cselect_b32 s0, 4, 11
	v_mul_f32_e32 v10, 0x3fb8aa3b, v10
	v_exp_f32_e32 v20, v10
	v_or_b32_e32 v10, s0, v0
	v_lshl_or_b32 v10, v10, 9, v56
	ds_read_b64 v[10:11], v10 offset:40960
	v_fma_mix_f32 v9, v9, v20, v13 op_sel_hi:[0,0,1]
	s_waitcnt lgkmcnt(0)
	v_cvt_f16_f32_e32 v12, v10
	v_cvt_f16_f32_e32 v13, v11
	v_cvt_pk_f16_f32 v15, v10, v11
	v_or_b32_e32 v10, s0, v6
	v_mov_b32_e32 v11, v7
	v_lshlrev_b64 v[10:11], 10, v[10:11]
	v_lshl_add_u64 v[10:11], v[4:5], 0, v[10:11]
	global_store_dword v[10:11], v15, off nt
	v_cvt_f32_f16_e32 v10, v12
	s_cselect_b32 s0, 5, 10
	v_or_b32_e32 v11, s0, v0
	v_lshl_or_b32 v11, v11, 9, v56
	v_mul_f32_e32 v10, 0x3fb8aa3b, v10
	v_exp_f32_e32 v10, v10
	s_nop 0
	v_fma_mix_f32 v9, v9, v10, v13 op_sel_hi:[0,0,1]
	ds_read_b64 v[12:13], v11 offset:40960
	s_waitcnt lgkmcnt(0)
	v_cvt_f16_f32_e32 v11, v12
	v_cvt_f16_f32_e32 v15, v13
	v_cvt_pk_f16_f32 v16, v12, v13
	v_or_b32_e32 v12, s0, v6
	v_cvt_f32_f16_e32 v11, v11
	v_mov_b32_e32 v13, v7
	s_cselect_b32 s0, 6, 9
	v_lshlrev_b64 v[12:13], 10, v[12:13]
	v_mul_f32_e32 v11, 0x3fb8aa3b, v11
	v_exp_f32_e32 v22, v11
	v_or_b32_e32 v11, s0, v0
	v_lshl_add_u64 v[12:13], v[4:5], 0, v[12:13]
	v_lshl_or_b32 v11, v11, 9, v56
	global_store_dword v[12:13], v16, off nt
	ds_read_b64 v[12:13], v11 offset:40960
	v_fma_mix_f32 v9, v9, v22, v15 op_sel_hi:[0,0,1]
	s_waitcnt lgkmcnt(0)
	v_cvt_f16_f32_e32 v11, v12
	v_cvt_f16_f32_e32 v15, v13
	v_cvt_pk_f16_f32 v16, v12, v13
	v_or_b32_e32 v12, s0, v6
	v_cvt_f32_f16_e32 v11, v11
	v_mov_b32_e32 v13, v7
	v_lshlrev_b64 v[12:13], 10, v[12:13]
	v_lshl_add_u64 v[12:13], v[4:5], 0, v[12:13]
	v_mul_f32_e32 v11, 0x3fb8aa3b, v11
	s_cselect_b32 s0, 7, 8
	global_store_dword v[12:13], v16, off nt
	v_exp_f32_e32 v12, v11
	v_or_b32_e32 v11, s0, v0
	v_lshl_or_b32 v11, v11, 9, v56
	ds_read_b64 v[16:17], v11 offset:40960
	v_fma_mix_f32 v9, v9, v12, v15 op_sel_hi:[0,0,1]
	s_waitcnt lgkmcnt(0)
	v_cvt_f16_f32_e32 v11, v16
	v_cvt_f16_f32_e32 v13, v17
	v_cvt_pk_f16_f32 v15, v16, v17
	v_or_b32_e32 v16, s0, v6
	v_cvt_f32_f16_e32 v11, v11
	v_mov_b32_e32 v17, v7
	s_cselect_b32 s0, 8, 7
	v_lshlrev_b64 v[16:17], 10, v[16:17]
	v_mul_f32_e32 v11, 0x3fb8aa3b, v11
	v_exp_f32_e32 v18, v11
	v_or_b32_e32 v11, s0, v0
	v_lshl_add_u64 v[16:17], v[4:5], 0, v[16:17]
	v_lshl_or_b32 v11, v11, 9, v56
	global_store_dword v[16:17], v15, off nt
	ds_read_b64 v[16:17], v11 offset:40960
	v_fma_mix_f32 v9, v9, v18, v13 op_sel_hi:[0,0,1]
	s_waitcnt lgkmcnt(0)
	v_cvt_f16_f32_e32 v11, v16
	v_cvt_f16_f32_e32 v13, v17
	v_cvt_pk_f16_f32 v15, v16, v17
	v_or_b32_e32 v16, s0, v6
	v_cvt_f32_f16_e32 v11, v11
	v_mov_b32_e32 v17, v7
	v_lshlrev_b64 v[16:17], 10, v[16:17]
	v_lshl_add_u64 v[16:17], v[4:5], 0, v[16:17]
	v_mul_f32_e32 v11, 0x3fb8aa3b, v11
	global_store_dword v[16:17], v15, off nt
	v_exp_f32_e32 v16, v11
	s_cselect_b32 s0, 9, 6
	v_fma_mix_f32 v15, v9, v16, v13 op_sel_hi:[0,0,1]
	v_or_b32_e32 v9, s0, v0
	v_lshl_or_b32 v9, v9, 9, v56
	ds_read_b64 v[80:81], v9 offset:40960
	s_waitcnt lgkmcnt(0)
	v_cvt_f16_f32_e32 v11, v81
	v_cvt_f16_f32_e32 v9, v80
	v_cvt_pk_f16_f32 v13, v80, v81
	v_or_b32_e32 v80, s0, v6
	v_mov_b32_e32 v81, v7
	s_cselect_b32 s0, 10, 5
	v_lshlrev_b64 v[80:81], 10, v[80:81]
	v_cvt_f32_f16_e32 v21, v11
	v_or_b32_e32 v11, s0, v0
	v_lshl_add_u64 v[80:81], v[4:5], 0, v[80:81]
	v_lshl_or_b32 v11, v11, 9, v56
	global_store_dword v[80:81], v13, off nt
	ds_read_b64 v[80:81], v11 offset:40960
	v_cvt_f32_f16_e32 v9, v9
	s_waitcnt lgkmcnt(0)
	v_cvt_f16_f32_e32 v11, v80
	v_mul_f32_e32 v9, 0x3fb8aa3b, v9
	v_cvt_f16_f32_e32 v13, v81
	v_exp_f32_e32 v9, v9
	v_cvt_f32_f16_e32 v11, v11
	v_cvt_pk_f16_f32 v17, v80, v81
	v_or_b32_e32 v80, s0, v6
	v_mov_b32_e32 v81, v7
	v_mul_f32_e32 v11, 0x3fb8aa3b, v11
	v_exp_f32_e32 v11, v11
	v_lshlrev_b64 v[80:81], 10, v[80:81]
	v_cvt_f32_f16_e32 v23, v13
	v_lshl_add_u64 v[80:81], v[4:5], 0, v[80:81]
	v_mul_f32_e32 v13, v14, v8
	v_pk_fma_f32 v[14:15], v[14:15], v[8:9], v[20:21]
	s_cselect_b32 s0, 11, 4
	global_store_dword v[80:81], v17, off nt
	v_mul_f32_e32 v80, v13, v20
	v_mov_b32_e32 v81, v15
	v_or_b32_e32 v8, s0, v0
	v_pk_mul_f32 v[14:15], v[80:81], v[10:11]
	v_lshl_or_b32 v8, v8, 9, v56
	v_pk_mul_f32 v[20:21], v[14:15], v[22:23]
	v_pk_fma_f32 v[14:15], v[80:81], v[10:11], v[22:23]
	ds_read_b64 v[22:23], v8 offset:40960
	v_mov_b32_e32 v14, v20
	s_waitcnt lgkmcnt(0)
; DI void lru_tile(const Params& P, int l, int b, int tile, int g, char* smem, bool final, const LruK& K) {
;     ...
; #pragma unroll
;       for (int e = 0; e < 16; e++) {
;         const int ee = dir == 0 ? e : 15 - e;
;         const float2 lb = ab[(tq * 16 + ee) * 64 + ch];
;         fp16x2 hv; hv[0] = (__fp16)lb.x; hv[1] = (__fp16)lb.y;
;         lab[((size_t)dir * TA + rowbase + t0 + tq * 16 + ee) * 256 + gc] = __builtin_bit_cast(unsigned, hv);
;         const float a = __expf((float)hv[0]), bt = (float)hv[1];
;         h = a * h + bt; A *= a;
;       }
;       subst[tq * 64 + ch] = make_float2(A, h);
;     }
;     __syncthreads();
;     if (tq == 0) {
;       float A = 1.f, h = 0.f;
; #pragma unroll
;       for (int s2 = 0; s2 < 4; s2++) { float2 ss = subst[(dir == 0 ? s2 : 3 - s2) * 64 + ch]; h = ss.x * h + ss.y; A *= ss.x; }
;       P.lsum[((size_t)((b * 2 + dir) * 132 + tile)) * 256 + gc] = make_float2(A, h);
;     }
	v_cvt_f16_f32_e32 v8, v22
	v_cvt_f16_f32_e32 v10, v23
	v_cvt_pk_f16_f32 v13, v22, v23
	v_or_b32_e32 v22, s0, v6
	v_cvt_f32_f16_e32 v8, v8
	v_mov_b32_e32 v23, v7
	v_lshlrev_b64 v[22:23], 10, v[22:23]
	v_lshl_add_u64 v[22:23], v[4:5], 0, v[22:23]
	v_mul_f32_e32 v8, 0x3fb8aa3b, v8
	s_cselect_b32 s0, 12, 3
	global_store_dword v[22:23], v13, off nt
	v_exp_f32_e32 v13, v8
	v_or_b32_e32 v8, s0, v0
	v_lshl_or_b32 v8, v8, 9, v56
	ds_read_b64 v[22:23], v8 offset:40960
	v_cvt_f32_f16_e32 v19, v10
	v_pk_mul_f32 v[20:21], v[20:21], v[12:13]
	v_mov_b32_e32 v82, v13
	s_waitcnt lgkmcnt(0)
	v_cvt_f16_f32_e32 v8, v22
	v_cvt_f16_f32_e32 v10, v23
	v_cvt_pk_f16_f32 v17, v22, v23
	v_or_b32_e32 v22, s0, v6
	v_cvt_f32_f16_e32 v8, v8
	v_mov_b32_e32 v23, v7
	v_lshlrev_b64 v[22:23], 10, v[22:23]
	v_lshl_add_u64 v[22:23], v[4:5], 0, v[22:23]
	v_mul_f32_e32 v8, 0x3fb8aa3b, v8
	s_cselect_b32 s0, 13, 2
	global_store_dword v[22:23], v17, off nt
	v_exp_f32_e32 v17, v8
	v_or_b32_e32 v8, s0, v0
	v_lshl_or_b32 v8, v8, 9, v56
	ds_read_b64 v[80:81], v8 offset:40960
	v_cvt_f32_f16_e32 v23, v10
	v_pk_mul_f32 v[20:21], v[20:21], v[18:19]
	v_pk_fma_f32 v[14:15], v[14:15], v[12:13], v[18:19]
	s_waitcnt lgkmcnt(0)
	v_cvt_f16_f32_e32 v8, v80
	v_cvt_f16_f32_e32 v10, v81
	v_cvt_pk_f16_f32 v22, v80, v81
	v_or_b32_e32 v80, s0, v6
	v_cvt_f32_f16_e32 v8, v8
	v_mov_b32_e32 v81, v7
	v_lshlrev_b64 v[80:81], 10, v[80:81]
	v_lshl_add_u64 v[80:81], v[4:5], 0, v[80:81]
	v_mul_f32_e32 v8, 0x3fb8aa3b, v8
	s_cselect_b32 s0, 14, 1
	global_store_dword v[80:81], v22, off nt
	v_exp_f32_e32 v81, v8
	v_or_b32_e32 v8, s0, v0
	v_lshl_or_b32 v8, v8, 9, v56
	ds_read_b64 v[84:85], v8 offset:40960
	v_cvt_f32_f16_e32 v83, v10
	v_mov_b32_e32 v21, v15
	v_pk_mul_f32 v[14:15], v[20:21], v[16:17]
	v_mov_b32_e32 v80, v11
	s_waitcnt lgkmcnt(0)
	v_cvt_f16_f32_e32 v8, v84
	v_cvt_f16_f32_e32 v10, v85
	v_cvt_pk_f16_f32 v22, v84, v85
	v_or_b32_e32 v84, s0, v6
	v_cvt_f32_f16_e32 v8, v8
	v_mov_b32_e32 v85, v7
	v_lshlrev_b64 v[84:85], 10, v[84:85]
	v_lshl_add_u64 v[84:85], v[4:5], 0, v[84:85]
	v_mul_f32_e32 v8, 0x3fb8aa3b, v8
	s_cselect_b32 s0, 15, 0
	global_store_dword v[84:85], v22, off nt
	v_exp_f32_e32 v85, v8
	v_or_b32_e32 v8, s0, v0
	v_lshl_or_b32 v8, v8, 9, v56
	ds_read_b64 v[88:89], v8 offset:40960
	v_or_b32_e32 v6, s0, v6
	v_lshlrev_b64 v[6:7], 10, v[6:7]
	v_lshl_add_u64 v[6:7], v[4:5], 0, v[6:7]
	v_cvt_f32_f16_e32 v87, v10
	s_waitcnt lgkmcnt(0)
	v_cvt_f16_f32_e32 v8, v88
	v_cvt_pk_f16_f32 v22, v88, v89
	global_store_dword v[6:7], v22, off nt
	v_cvt_f16_f32_e32 v10, v89
	v_cvt_f32_f16_e32 v6, v8
	v_mov_b32_e32 v22, v9
	v_mov_b32_e32 v84, v17
	v_cvt_f32_f16_e32 v89, v10
	v_mul_f32_e32 v6, 0x3fb8aa3b, v6
	v_exp_f32_e32 v7, v6
	v_mov_b32_e32 v6, v9
	v_mov_b32_e32 v86, v81
	v_mov_b32_e32 v12, v85
	v_pk_mul_f32 v[8:9], v[14:15], v[6:7]
	v_pk_fma_f32 v[14:15], v[20:21], v[16:17], v[22:23]
	v_mov_b32_e32 v6, v11
	v_mov_b32_e32 v14, v8
	v_pk_mul_f32 v[8:9], v[8:9], v[6:7]
	v_mov_b32_e32 v6, v13
	v_pk_mul_f32 v[8:9], v[8:9], v[6:7]
	v_pk_fma_f32 v[10:11], v[14:15], v[80:81], v[82:83]
	v_mov_b32_e32 v6, v81
	v_mov_b32_e32 v9, v11
	v_pk_mul_f32 v[10:11], v[8:9], v[84:85]
	v_pk_fma_f32 v[8:9], v[8:9], v[84:85], v[86:87]
	v_pk_mul_f32 v[10:11], v[10:11], v[6:7]
	v_mov_b32_e32 v6, v85
	v_mov_b32_e32 v8, v10
	v_pk_mul_f32 v[10:11], v[10:11], v[12:13]
	v_mov_b32_e32 v12, v7
	v_mov_b32_e32 v88, v7
	v_pk_mul_f32 v[10:11], v[10:11], v[12:13]
	v_pk_fma_f32 v[6:7], v[8:9], v[6:7], v[88:89]
	s_nop 0
	v_mov_b32_e32 v11, v7
	ds_write_b64 v1, v[10:11]
	s_waitcnt lgkmcnt(0)
	s_barrier
	s_and_saveexec_b64 s[0:1], s[4:5]
	s_cbranch_execz .LBB0_400
	s_and_b64 s[6:7], s[2:3], exec
	s_cselect_b32 s6, 0, 0x600
	v_add_u32_e32 v6, s6, v1
	s_cselect_b32 s6, s43, 0x400
	v_add_u32_e32 v8, s6, v1
	s_cselect_b32 s6, 0x400, s43
	v_add_u32_e32 v10, s6, v1
	s_cselect_b32 s6, 0x600, 0
	ds_read_b64 v[6:7], v6
	ds_read_b64 v[8:9], v8
	v_add_u32_e32 v12, s6, v1
	ds_read_b64 v[10:11], v10
	ds_read_b64 v[12:13], v12
	s_or_b32 s6, s20, s11
	s_waitcnt lgkmcnt(3)
	v_fma_f32 v7, 0, v6, v7
	s_waitcnt lgkmcnt(2)
	v_fmac_f32_e32 v9, v7, v8
	v_mul_f32_e32 v6, v6, v8
	s_waitcnt lgkmcnt(1)
	v_fma_f32 v7, v9, v10, v11
	s_mulk_i32 s6, 0x84
	s_waitcnt lgkmcnt(0)
	v_mov_b32_e32 v11, v12
	s_add_i32 s6, s6, s9
	v_pk_mul_f32 v[14:15], v[6:7], v[10:11]
	v_lshl_or_b32 v148, s6, 8, v53
	v_pk_mul_f32 v[14:15], v[14:15], v[12:13]
	v_pk_fma_f32 v[6:7], v[6:7], v[10:11], v[12:13]
	v_lshl_add_u64 v[8:9], v[148:149], 3, s[70:71]
	v_mov_b32_e32 v15, v7
	global_store_dwordx2 v[8:9], v[14:15], off
	s_branch .LBB0_400
